# S2 balanced DMA issue in all 4 big GEMM K-loops + LN DPP/vmcnt changes
# baseline (speedup 1.0000x reference)
; #define PG8_STAGE(bufoff, gbase, voff) do { _Pragma("unroll") for (int _i = 0; _i < 2; ++_i) \
;         __builtin_amdgcn_global_load_lds((const unsigned*)((const char*)(gbase) + (voff)[_i]), (LAS unsigned*)(lds + (bufoff) + ldsw + _i * 8192), 16, 0, 0); } while (0)
; #define PG8_WAIT_V(n) asm volatile("s_waitcnt vmcnt(" #n ")" ::: "memory")
; #define PG8_BAR __builtin_amdgcn_s_barrier()
; template <class Epi, class Sched>
; __device__ __forceinline__ void gemm_phase(LAS unsigned char* lds, const Gemm g, const Sched& S, const Epi& E) {
;     ...
;     PG8_STAGE(PG8_SB(1, 0), cB + kstep, voffB); PG8_STAGE(PG8_SA(1, 0), cA + kstep, voffA); PG8_STAGE(PG8_SB(1, 1), cB + hstep + kstep, voffB);
;     PG8_WAIT_V(6); PG8_BAR;
;     for (;;) {
;         const bool has_next = S.next(ui + 1, nxt);
;         const char* nA = has_next ? (const char*)g.A + (size_t)nxt.pm * tstep : cA; const char* nB = has_next ? (const char*)g.Bt + (size_t)nxt.pn * tstep : cB;
;         for (int t = 0; t < nt; t += 2) {
;             const bool last = (t == nt - 2);
;             const char* a1 = cA + (size_t)(t + 1) * kstep;
;             const char* a2 = last ? nA : cA + (size_t)(t + 2) * kstep; const char* b2 = last ? nB : cB + (size_t)(t + 2) * kstep;
;     __device__ __forceinline__ void operator()(const f32x4 (&acc)[2][2][4][2], const Unit& u, int wr, int wc, int fr, int fq) const {
;         char* p = (char*)(O + (size_t)(wr * 64 + fr) * ldc + u.pn * BM + wc * 32 + 8 * fq);
.LBB0_124:
	s_add_u32 s36, s44, s88
	s_addc_u32 s38, s45, s89
	s_add_u32 s46, s36, 0xe000000
	s_addc_u32 s47, s38, 0
	s_add_i32 m0, s5, 0x18000
	v_lshl_add_u64 v[10:11], v[10:11], 0, s[6:7]
	s_waitcnt vmcnt(2)
	s_barrier
	global_load_lds_dwordx4 v[10:11], off
	v_lshl_add_u64 v[6:7], v[6:7], 0, s[6:7]
	s_add_i32 m0, s5, 0x1a000
	s_add_i32 s53, s5, 0x8000
	global_load_lds_dwordx4 v[6:7], off
	v_lshl_add_u64 v[6:7], v[8:9], 0, s[6:7]
	s_mov_b32 m0, s53
	s_add_i32 s54, s5, 0xa000
	global_load_lds_dwordx4 v[6:7], off
	v_lshl_add_u64 v[6:7], v[12:13], 0, s[6:7]
	s_mov_b32 m0, s54
	global_load_lds_dwordx4 v[6:7], off
	s_add_i32 m0, s5, 0x1c000
	v_mov_b64_e32 v[216:217], v[4:5]
	s_add_i32 m0, s5, 0x1e000
	s_lshr_b32 s36, s41, 26
	v_mov_b64_e32 v[238:239], v[2:3]
	s_add_i32 s36, s40, s36
	s_lshl_b32 s8, s8, 5
	v_and_b32_e32 v3, 15, v14
	s_ashr_i32 s55, s36, 6
	s_and_b32 s36, s8, 0x60
	s_lshl_b64 s[38:39], s[40:41], 9
	v_lshl_or_b32 v6, s9, 6, v3
	s_lshl_b32 s9, s9, 13
	s_lshl_b32 s8, s36, 7
	v_and_b32_e32 v2, 48, v14
	v_lshlrev_b32_e32 v4, 2, v14
	s_cmp_gt_i32 s40, 63
	v_lshl_or_b32 v3, v3, 6, v2
	v_and_b32_e32 v4, 32, v4
	s_cselect_b64 s[40:41], -1, 0
	s_add_i32 s56, s55, -2
	v_bitop3_b32 v7, v3, s9, v4 bitop3:0xde
	v_bitop3_b32 v142, v3, s8, v4 bitop3:0xde
	s_cmpk_lt_u32 s1, 0x100
	v_mov_b64_e32 v[4:5], s[46:47]
	s_cselect_b64 s[42:43], -1, 0
	v_mad_i64_i32 v[4:5], s[8:9], v6, s90, v[4:5]
	s_lshl_b32 s36, s36, 1
	v_readlane_b32 s1, v248, 14
	s_add_u32 s1, s44, s1
	v_readlane_b32 s8, v248, 15
	v_lshl_add_u64 v[4:5], v[4:5], 0, s[36:37]
	v_mov_b32_e32 v3, v1
	s_addc_u32 s9, s45, s8
	v_lshl_add_u64 v[136:137], v[4:5], 0, v[2:3]
	v_add_u32_e32 v2, v20, v18
	s_add_u32 s8, s1, s20
	v_add_lshl_u32 v2, v2, v19, 1
	s_addc_u32 s9, s9, s21
	s_waitcnt vmcnt(4)
	v_lshl_add_u64 v[138:139], s[8:9], 0, v[2:3]
	v_add_u32_e32 v2, v17, v15
	v_add_lshl_u32 v2, v2, v16, 1
	v_lshl_add_u64 v[140:141], s[8:9], 0, v[2:3]
	s_mov_b32 s8, 0
	v_add_u32_e32 v143, 0, v7
	s_mov_b64 s[46:47], s[10:11]
	s_mov_b64 s[44:45], s[10:11]
	s_barrier
	s_branch .LBB0_127

; #define PG8_STAGE(bufoff, gbase, voff) do { _Pragma("unroll") for (int _i = 0; _i < 2; ++_i) \
;         __builtin_amdgcn_global_load_lds((const unsigned*)((const char*)(gbase) + (voff)[_i]), (LAS unsigned*)(lds + (bufoff) + ldsw + _i * 8192), 16, 0, 0); } while (0)
; #define PG8_LDA(dst, b, h) do { _Pragma("unroll") for (int m = 0; m < 4; ++m) _Pragma("unroll") for (int k = 0; k < 2; ++k) dst[m][k] = *(const LAS bf16x8*)(lds + PG8_SA(b, h) + aoff + m * 2048 + k * 1024); } while (0)
; #define PG8_LDB(dst, b, h) do { _Pragma("unroll") for (int n = 0; n < 2; ++n) _Pragma("unroll") for (int k = 0; k < 2; ++k) dst[n][k] = *(const LAS bf16x8*)(lds + PG8_SB(b, h) + boff + n * 2048 + k * 1024); } while (0)
; #define PG8_MMA(ai, bj, At, Bt) do { __builtin_amdgcn_s_setprio(1); _Pragma("unroll") for (int m = 0; m < 4; ++m) _Pragma("unroll") for (int n = 0; n < 2; ++n) _Pragma("unroll") for (int k = 0; k < 2; ++k) \
;         acc[ai][bj][m][n] = __builtin_amdgcn_mfma_f32_16x16x32_bf16(Bt[n][k], At[m][k], acc[ai][bj][m][n], 0, 0, 0); __builtin_amdgcn_s_setprio(0); } while (0)
; #define PG8_WAIT_V(n) asm volatile("s_waitcnt vmcnt(" #n ")" ::: "memory")
; #define PG8_WAIT_L(n) asm volatile("s_waitcnt lgkmcnt(" #n ")" ::: "memory")
; #define PG8_BAR __builtin_amdgcn_s_barrier()
; #define PG8_SCHED __builtin_amdgcn_sched_barrier(0)
; template <class Epi, class Sched>
; __device__ __forceinline__ void gemm_phase(LAS unsigned char* lds, const Gemm g, const Sched& S, const Epi& E) {
;     ...
;             PG8_LDB(B0, 0, 0); PG8_LDB(B1, 0, 1); PG8_SCHED; PG8_LDA(At, 0, 0); PG8_STAGE(PG8_SA(1, 1), a1 + hstep, voffA);
;             PG8_WAIT_V(8); PG8_WAIT_L(0); PG8_BAR; PG8_MMA(0, 0, At, B0); PG8_MMA(0, 1, At, B1); PG8_BAR; PG8_SCHED;
;             PG8_LDA(At, 0, 1); PG8_STAGE(PG8_SB(0, 0), b2, voffB); PG8_STAGE(PG8_SB(0, 1), b2 + hstep, voffB); PG8_STAGE(PG8_SA(0, 0), a2, voffA);
;             PG8_WAIT_V(8); PG8_WAIT_L(0); PG8_BAR; PG8_MMA(1, 0, At, B0); PG8_MMA(1, 1, At, B1); PG8_BAR; PG8_SCHED;
.LBB0_131:
	s_add_i32 s58, s50, 2
	s_add_u32 s48, s46, 0x100
	s_addc_u32 s49, s47, 0
	s_add_u32 s1, s9, s46
	s_addc_u32 s51, s36, s47
	s_cmp_eq_u32 s56, s50
	s_cselect_b32 s50, 0, s48
	s_cselect_b32 s59, 0, s49
	s_cselect_b32 s60, s44, s1
	s_cselect_b32 s61, s45, s51
	s_add_u32 s50, s2, s50
	s_addc_u32 s51, s3, s59
	s_add_i32 s1, 0, 0x10000
	s_add_i32 s59, 0, 0x14000
	v_add_u32_e32 v156, s1, v142
	v_add_u32_e32 v172, s59, v142
	ds_read_b128 v[144:147], v156
	ds_read_b128 v[148:151], v156 offset:1024
	ds_read_b128 v[152:155], v156 offset:2048
	ds_read_b128 v[156:159], v156 offset:3072
	ds_read_b128 v[160:163], v172
	ds_read_b128 v[164:167], v172 offset:1024
	ds_read_b128 v[168:171], v172 offset:2048
	ds_read_b128 v[172:175], v172 offset:3072
	v_lshl_add_u64 v[212:213], v[216:217], 0, s[6:7]
	s_add_i32 m0, s4, 0x1c000
	s_nop 0
	global_load_lds_dwordx4 v[212:213], off
	v_lshl_add_u64 v[212:213], v[238:239], 0, s[6:7]
	s_add_i32 m0, s4, 0x1e000
	s_nop 0
	global_load_lds_dwordx4 v[212:213], off
	v_lshl_add_u64 v[212:213], v[138:139], 0, s[46:47]
	s_add_i32 m0, s5, 0xc000
	ds_read_b128 v[176:179], v143
	ds_read_b128 v[180:183], v143 offset:1024
	ds_read_b128 v[184:187], v143 offset:2048
	ds_read_b128 v[192:195], v143 offset:3072
	ds_read_b128 v[196:199], v143 offset:4096
	ds_read_b128 v[200:203], v143 offset:5120
	ds_read_b128 v[204:207], v143 offset:6144
	ds_read_b128 v[208:211], v143 offset:7168
	global_load_lds_dwordx4 v[212:213], off
	v_lshl_add_u64 v[212:213], v[140:141], 0, s[46:47]
	s_add_i32 m0, s5, 0xe000
	s_nop 0
	global_load_lds_dwordx4 v[212:213], off
	s_waitcnt vmcnt(8)
	s_waitcnt lgkmcnt(0)
	s_barrier
	s_setprio 1
	s_waitcnt lgkmcnt(0)
	v_mfma_f32_16x16x32_bf16 v[122:125], v[144:147], v[176:179], v[122:125]
	v_mfma_f32_16x16x32_bf16 v[126:129], v[152:155], v[176:179], v[126:129]
	v_mfma_f32_16x16x32_bf16 v[110:113], v[144:147], v[184:187], v[110:113]
	v_mfma_f32_16x16x32_bf16 v[106:109], v[152:155], v[184:187], v[106:109]
	v_mfma_f32_16x16x32_bf16 v[94:97], v[144:147], v[196:199], v[94:97]
	v_mfma_f32_16x16x32_bf16 v[90:93], v[152:155], v[196:199], v[90:93]
	v_mfma_f32_16x16x32_bf16 v[78:81], v[144:147], v[204:207], v[78:81]
	v_mfma_f32_16x16x32_bf16 v[74:77], v[152:155], v[204:207], v[74:77]
	v_mfma_f32_16x16x32_bf16 v[122:125], v[148:151], v[180:183], v[122:125]
	v_mfma_f32_16x16x32_bf16 v[126:129], v[156:159], v[180:183], v[126:129]
	v_mfma_f32_16x16x32_bf16 v[110:113], v[148:151], v[192:195], v[110:113]
	v_mfma_f32_16x16x32_bf16 v[106:109], v[156:159], v[192:195], v[106:109]
	v_mfma_f32_16x16x32_bf16 v[94:97], v[148:151], v[200:203], v[94:97]
	v_mfma_f32_16x16x32_bf16 v[90:93], v[156:159], v[200:203], v[90:93]
	v_mfma_f32_16x16x32_bf16 v[78:81], v[148:151], v[208:211], v[78:81]
	v_mfma_f32_16x16x32_bf16 v[74:77], v[156:159], v[208:211], v[74:77]
	s_setprio 0
	s_setprio 1
	v_mfma_f32_16x16x32_bf16 v[118:121], v[160:163], v[176:179], v[118:121]
	v_mfma_f32_16x16x32_bf16 v[114:117], v[168:171], v[176:179], v[114:117]
	v_mfma_f32_16x16x32_bf16 v[102:105], v[160:163], v[184:187], v[102:105]
	v_mfma_f32_16x16x32_bf16 v[98:101], v[168:171], v[184:187], v[98:101]
	v_mfma_f32_16x16x32_bf16 v[86:89], v[160:163], v[196:199], v[86:89]
	v_mfma_f32_16x16x32_bf16 v[82:85], v[168:171], v[196:199], v[82:85]
	v_mfma_f32_16x16x32_bf16 v[70:73], v[160:163], v[204:207], v[70:73]
	v_mfma_f32_16x16x32_bf16 v[66:69], v[168:171], v[204:207], v[66:69]
	v_mfma_f32_16x16x32_bf16 v[118:121], v[164:167], v[180:183], v[118:121]
	v_mfma_f32_16x16x32_bf16 v[114:117], v[172:175], v[180:183], v[114:117]
	v_mfma_f32_16x16x32_bf16 v[102:105], v[164:167], v[192:195], v[102:105]
	v_mfma_f32_16x16x32_bf16 v[98:101], v[172:175], v[192:195], v[98:101]
	v_mfma_f32_16x16x32_bf16 v[86:89], v[164:167], v[200:203], v[86:89]
	v_mfma_f32_16x16x32_bf16 v[82:85], v[172:175], v[200:203], v[82:85]
	v_mfma_f32_16x16x32_bf16 v[70:73], v[164:167], v[208:211], v[70:73]
	v_mfma_f32_16x16x32_bf16 v[66:69], v[172:175], v[208:211], v[66:69]
	s_setprio 0
	s_barrier
	s_add_i32 s1, s1, s4
	v_lshl_add_u64 v[212:213], s[60:61], 0, v[0:1]
	s_mov_b32 m0, s1
	ds_read_b128 v[176:179], v143 offset:16384
	ds_read_b128 v[180:183], v143 offset:17408
	ds_read_b128 v[184:187], v143 offset:18432
	ds_read_b128 v[192:195], v143 offset:19456
	ds_read_b128 v[196:199], v143 offset:20480
	ds_read_b128 v[200:203], v143 offset:21504
	ds_read_b128 v[204:207], v143 offset:22528
	ds_read_b128 v[208:211], v143 offset:23552
	global_load_lds_dwordx4 v[212:213], off
	s_add_i32 m0, s1, 0x2000
	s_add_u32 s46, s60, s20
	v_lshl_add_u64 v[214:215], s[60:61], 0, v[130:131]
	s_addc_u32 s47, s61, s21
	s_add_i32 s1, s59, s4
	global_load_lds_dwordx4 v[214:215], off
	v_lshl_add_u64 v[216:217], s[46:47], 0, v[0:1]
	s_mov_b32 m0, s1
	v_lshl_add_u64 v[238:239], s[46:47], 0, v[130:131]
	s_add_i32 m0, s1, 0x2000
	v_lshl_add_u64 v[240:241], s[50:51], 0, v[134:135]
	s_mov_b32 m0, s5
	v_lshl_add_u64 v[244:245], s[50:51], 0, v[132:133]
	global_load_lds_dwordx4 v[240:241], off
	s_mov_b32 m0, s18
	s_nop 0
	global_load_lds_dwordx4 v[244:245], off
	s_waitcnt vmcnt(6)
	s_waitcnt lgkmcnt(0)
	s_barrier
; #define PG8_STAGE(bufoff, gbase, voff) do { _Pragma("unroll") for (int _i = 0; _i < 2; ++_i) \
;         __builtin_amdgcn_global_load_lds((const unsigned*)((const char*)(gbase) + (voff)[_i]), (LAS unsigned*)(lds + (bufoff) + ldsw + _i * 8192), 16, 0, 0); } while (0)
; #define PG8_LDA(dst, b, h) do { _Pragma("unroll") for (int m = 0; m < 4; ++m) _Pragma("unroll") for (int k = 0; k < 2; ++k) dst[m][k] = *(const LAS bf16x8*)(lds + PG8_SA(b, h) + aoff + m * 2048 + k * 1024); } while (0)
; #define PG8_LDB(dst, b, h) do { _Pragma("unroll") for (int n = 0; n < 2; ++n) _Pragma("unroll") for (int k = 0; k < 2; ++k) dst[n][k] = *(const LAS bf16x8*)(lds + PG8_SB(b, h) + boff + n * 2048 + k * 1024); } while (0)
; #define PG8_MMA(ai, bj, At, Bt) do { __builtin_amdgcn_s_setprio(1); _Pragma("unroll") for (int m = 0; m < 4; ++m) _Pragma("unroll") for (int n = 0; n < 2; ++n) _Pragma("unroll") for (int k = 0; k < 2; ++k) \
;         acc[ai][bj][m][n] = __builtin_amdgcn_mfma_f32_16x16x32_bf16(Bt[n][k], At[m][k], acc[ai][bj][m][n], 0, 0, 0); __builtin_amdgcn_s_setprio(0); } while (0)
; #define PG8_WAIT_V(n) asm volatile("s_waitcnt vmcnt(" #n ")" ::: "memory")
; #define PG8_WAIT_L(n) asm volatile("s_waitcnt lgkmcnt(" #n ")" ::: "memory")
; #define PG8_BAR __builtin_amdgcn_s_barrier()
; #define PG8_SCHED __builtin_amdgcn_sched_barrier(0)
; template <class Epi, class Sched>
; __device__ __forceinline__ void gemm_phase(LAS unsigned char* lds, const Gemm g, const Sched& S, const Epi& E) {
;     ...
;             PG8_WAIT_V(8); PG8_WAIT_L(0); PG8_BAR; PG8_MMA(1, 0, At, B0); PG8_MMA(1, 1, At, B1); PG8_BAR; PG8_SCHED;
;             PG8_LDB(B0, 1, 0); PG8_LDB(B1, 1, 1); PG8_SCHED; PG8_LDA(At, 1, 0); PG8_STAGE(PG8_SA(0, 1), a2 + hstep, voffA);
;             PG8_WAIT_V(8); PG8_WAIT_L(0); PG8_BAR; PG8_MMA(0, 0, At, B0); PG8_MMA(0, 1, At, B1); PG8_BAR; PG8_SCHED;
	s_setprio 1
	s_waitcnt lgkmcnt(0)
	v_mfma_f32_16x16x32_bf16 v[62:65], v[144:147], v[176:179], v[62:65]
	v_mfma_f32_16x16x32_bf16 v[58:61], v[152:155], v[176:179], v[58:61]
	v_mfma_f32_16x16x32_bf16 v[46:49], v[144:147], v[184:187], v[46:49]
	v_mfma_f32_16x16x32_bf16 v[42:45], v[152:155], v[184:187], v[42:45]
	v_mfma_f32_16x16x32_bf16 v[30:33], v[144:147], v[196:199], v[30:33]
	v_mfma_f32_16x16x32_bf16 v[26:29], v[152:155], v[196:199], v[26:29]
	v_mfma_f32_16x16x32_bf16 v[14:17], v[144:147], v[204:207], v[14:17]
	v_mfma_f32_16x16x32_bf16 v[10:13], v[152:155], v[204:207], v[10:13]
	v_mfma_f32_16x16x32_bf16 v[62:65], v[148:151], v[180:183], v[62:65]
	v_mfma_f32_16x16x32_bf16 v[58:61], v[156:159], v[180:183], v[58:61]
	v_mfma_f32_16x16x32_bf16 v[46:49], v[148:151], v[192:195], v[46:49]
	v_mfma_f32_16x16x32_bf16 v[42:45], v[156:159], v[192:195], v[42:45]
	v_mfma_f32_16x16x32_bf16 v[30:33], v[148:151], v[200:203], v[30:33]
	v_mfma_f32_16x16x32_bf16 v[26:29], v[156:159], v[200:203], v[26:29]
	v_mfma_f32_16x16x32_bf16 v[14:17], v[148:151], v[208:211], v[14:17]
	v_mfma_f32_16x16x32_bf16 v[10:13], v[156:159], v[208:211], v[10:13]
	s_setprio 0
	s_setprio 1
	v_mfma_f32_16x16x32_bf16 v[54:57], v[160:163], v[176:179], v[54:57]
	v_mfma_f32_16x16x32_bf16 v[50:53], v[168:171], v[176:179], v[50:53]
	v_mfma_f32_16x16x32_bf16 v[38:41], v[160:163], v[184:187], v[38:41]
	v_mfma_f32_16x16x32_bf16 v[34:37], v[168:171], v[184:187], v[34:37]
	v_mfma_f32_16x16x32_bf16 v[22:25], v[160:163], v[196:199], v[22:25]
	v_mfma_f32_16x16x32_bf16 v[18:21], v[168:171], v[196:199], v[18:21]
	v_mfma_f32_16x16x32_bf16 v[6:9], v[160:163], v[204:207], v[6:9]
	v_mfma_f32_16x16x32_bf16 v[2:5], v[168:171], v[204:207], v[2:5]
	v_mfma_f32_16x16x32_bf16 v[54:57], v[164:167], v[180:183], v[54:57]
	v_mfma_f32_16x16x32_bf16 v[50:53], v[172:175], v[180:183], v[50:53]
	v_mfma_f32_16x16x32_bf16 v[38:41], v[164:167], v[192:195], v[38:41]
	v_mfma_f32_16x16x32_bf16 v[34:37], v[172:175], v[192:195], v[34:37]
	v_mfma_f32_16x16x32_bf16 v[22:25], v[164:167], v[200:203], v[22:25]
	v_mfma_f32_16x16x32_bf16 v[18:21], v[172:175], v[200:203], v[18:21]
	v_mfma_f32_16x16x32_bf16 v[6:9], v[164:167], v[208:211], v[6:9]
	v_mfma_f32_16x16x32_bf16 v[2:5], v[172:175], v[208:211], v[2:5]
	s_setprio 0
	s_barrier
	s_add_i32 s1, 0, 0x18000
	s_add_i32 s59, 0, 0x1c000
	v_add_u32_e32 v156, s1, v142
	v_add_u32_e32 v172, s59, v142
	ds_read_b128 v[144:147], v156
	ds_read_b128 v[148:151], v156 offset:1024
	ds_read_b128 v[152:155], v156 offset:2048
	ds_read_b128 v[156:159], v156 offset:3072
	ds_read_b128 v[160:163], v172
	ds_read_b128 v[164:167], v172 offset:1024
	ds_read_b128 v[168:171], v172 offset:2048
	ds_read_b128 v[172:175], v172 offset:3072
	s_add_i32 m0, s4, 0x14000
	s_nop 0
	global_load_lds_dwordx4 v[216:217], off
	s_add_i32 m0, s4, 0x16000
	s_nop 0
	global_load_lds_dwordx4 v[238:239], off
	s_add_u32 s46, s50, s20
	s_addc_u32 s47, s51, s21
	s_mov_b32 m0, s19
	v_lshl_add_u64 v[246:247], s[46:47], 0, v[134:135]
	ds_read_b128 v[176:179], v143 offset:32768
	ds_read_b128 v[180:183], v143 offset:33792
	ds_read_b128 v[184:187], v143 offset:34816
	ds_read_b128 v[192:195], v143 offset:35840
	ds_read_b128 v[196:199], v143 offset:36864
	ds_read_b128 v[200:203], v143 offset:37888
	ds_read_b128 v[204:207], v143 offset:38912
	ds_read_b128 v[208:211], v143 offset:39936
	global_load_lds_dwordx4 v[246:247], off
	v_lshl_add_u64 v[246:247], s[46:47], 0, v[132:133]
	s_mov_b32 m0, s52
	s_nop 0
	global_load_lds_dwordx4 v[246:247], off
	s_waitcnt vmcnt(8)
	s_waitcnt lgkmcnt(0)
	s_barrier
; #define PG8_STAGE(bufoff, gbase, voff) do { _Pragma("unroll") for (int _i = 0; _i < 2; ++_i) \
;         __builtin_amdgcn_global_load_lds((const unsigned*)((const char*)(gbase) + (voff)[_i]), (LAS unsigned*)(lds + (bufoff) + ldsw + _i * 8192), 16, 0, 0); } while (0)
; #define PG8_LDA(dst, b, h) do { _Pragma("unroll") for (int m = 0; m < 4; ++m) _Pragma("unroll") for (int k = 0; k < 2; ++k) dst[m][k] = *(const LAS bf16x8*)(lds + PG8_SA(b, h) + aoff + m * 2048 + k * 1024); } while (0)
; #define PG8_MMA(ai, bj, At, Bt) do { __builtin_amdgcn_s_setprio(1); _Pragma("unroll") for (int m = 0; m < 4; ++m) _Pragma("unroll") for (int n = 0; n < 2; ++n) _Pragma("unroll") for (int k = 0; k < 2; ++k) \
;         acc[ai][bj][m][n] = __builtin_amdgcn_mfma_f32_16x16x32_bf16(Bt[n][k], At[m][k], acc[ai][bj][m][n], 0, 0, 0); __builtin_amdgcn_s_setprio(0); } while (0)
; #define PG8_WAIT_V(n) asm volatile("s_waitcnt vmcnt(" #n ")" ::: "memory")
; #define PG8_WAIT_L(n) asm volatile("s_waitcnt lgkmcnt(" #n ")" ::: "memory")
; #define PG8_BAR __builtin_amdgcn_s_barrier()
; #define PG8_SCHED __builtin_amdgcn_sched_barrier(0)
; template <class Epi, class Sched>
; __device__ __forceinline__ void gemm_phase(LAS unsigned char* lds, const Gemm g, const Sched& S, const Epi& E) {
;     ...
;             PG8_WAIT_V(8); PG8_WAIT_L(0); PG8_BAR; PG8_MMA(0, 0, At, B0); PG8_MMA(0, 1, At, B1); PG8_BAR; PG8_SCHED;
;             PG8_LDA(At, 1, 1); PG8_STAGE(PG8_SB(1, 0), b3, voffB); PG8_STAGE(PG8_SB(1, 1), b3 + hstep, voffB); PG8_STAGE(PG8_SA(1, 0), a3, voffA);
;             PG8_WAIT_V(8); PG8_WAIT_L(0); PG8_BAR; PG8_MMA(1, 0, At, B0); PG8_MMA(1, 1, At, B1); PG8_BAR; PG8_SCHED;
;         }
	s_setprio 1
	s_waitcnt lgkmcnt(0)
	v_mfma_f32_16x16x32_bf16 v[122:125], v[144:147], v[176:179], v[122:125]
	v_mfma_f32_16x16x32_bf16 v[126:129], v[152:155], v[176:179], v[126:129]
	v_mfma_f32_16x16x32_bf16 v[110:113], v[144:147], v[184:187], v[110:113]
	v_mfma_f32_16x16x32_bf16 v[106:109], v[152:155], v[184:187], v[106:109]
	v_mfma_f32_16x16x32_bf16 v[94:97], v[144:147], v[196:199], v[94:97]
	v_mfma_f32_16x16x32_bf16 v[90:93], v[152:155], v[196:199], v[90:93]
	v_mfma_f32_16x16x32_bf16 v[78:81], v[144:147], v[204:207], v[78:81]
	v_mfma_f32_16x16x32_bf16 v[74:77], v[152:155], v[204:207], v[74:77]
	v_mfma_f32_16x16x32_bf16 v[122:125], v[148:151], v[180:183], v[122:125]
	v_mfma_f32_16x16x32_bf16 v[126:129], v[156:159], v[180:183], v[126:129]
	v_mfma_f32_16x16x32_bf16 v[110:113], v[148:151], v[192:195], v[110:113]
	v_mfma_f32_16x16x32_bf16 v[106:109], v[156:159], v[192:195], v[106:109]
	v_mfma_f32_16x16x32_bf16 v[94:97], v[148:151], v[200:203], v[94:97]
	v_mfma_f32_16x16x32_bf16 v[90:93], v[156:159], v[200:203], v[90:93]
	v_mfma_f32_16x16x32_bf16 v[78:81], v[148:151], v[208:211], v[78:81]
	v_mfma_f32_16x16x32_bf16 v[74:77], v[156:159], v[208:211], v[74:77]
	s_setprio 0
	s_setprio 1
	v_mfma_f32_16x16x32_bf16 v[118:121], v[160:163], v[176:179], v[118:121]
	v_mfma_f32_16x16x32_bf16 v[114:117], v[168:171], v[176:179], v[114:117]
	v_mfma_f32_16x16x32_bf16 v[102:105], v[160:163], v[184:187], v[102:105]
	v_mfma_f32_16x16x32_bf16 v[98:101], v[168:171], v[184:187], v[98:101]
	v_mfma_f32_16x16x32_bf16 v[86:89], v[160:163], v[196:199], v[86:89]
	v_mfma_f32_16x16x32_bf16 v[82:85], v[168:171], v[196:199], v[82:85]
	v_mfma_f32_16x16x32_bf16 v[70:73], v[160:163], v[204:207], v[70:73]
	v_mfma_f32_16x16x32_bf16 v[66:69], v[168:171], v[204:207], v[66:69]
	v_mfma_f32_16x16x32_bf16 v[118:121], v[164:167], v[180:183], v[118:121]
	v_mfma_f32_16x16x32_bf16 v[114:117], v[172:175], v[180:183], v[114:117]
	v_mfma_f32_16x16x32_bf16 v[102:105], v[164:167], v[192:195], v[102:105]
	v_mfma_f32_16x16x32_bf16 v[98:101], v[172:175], v[192:195], v[98:101]
	v_mfma_f32_16x16x32_bf16 v[86:89], v[164:167], v[200:203], v[86:89]
	v_mfma_f32_16x16x32_bf16 v[82:85], v[172:175], v[200:203], v[82:85]
	v_mfma_f32_16x16x32_bf16 v[70:73], v[164:167], v[208:211], v[70:73]
	v_mfma_f32_16x16x32_bf16 v[66:69], v[172:175], v[208:211], v[66:69]
	s_setprio 0
	s_barrier
	s_add_i32 s1, s1, s4
	v_lshl_add_u64 v[212:213], v[212:213], 0, s[6:7]
	s_mov_b32 m0, s1
	ds_read_b128 v[176:179], v143 offset:49152
	ds_read_b128 v[180:183], v143 offset:50176
	ds_read_b128 v[184:187], v143 offset:51200
	ds_read_b128 v[192:195], v143 offset:52224
	ds_read_b128 v[196:199], v143 offset:53248
	ds_read_b128 v[200:203], v143 offset:54272
	ds_read_b128 v[204:207], v143 offset:55296
	ds_read_b128 v[208:211], v143 offset:56320
	global_load_lds_dwordx4 v[212:213], off
	v_lshl_add_u64 v[212:213], v[214:215], 0, s[6:7]
	s_add_i32 m0, s1, 0x2000
	s_add_i32 s1, s59, s4
	global_load_lds_dwordx4 v[212:213], off
	v_lshl_add_u64 v[212:213], v[216:217], 0, s[6:7]
	s_mov_b32 m0, s1
	s_nop 0
	v_lshl_add_u64 v[212:213], v[238:239], 0, s[6:7]
	s_add_i32 m0, s1, 0x2000
	s_nop 0
	v_lshl_add_u64 v[212:213], v[240:241], 0, s[6:7]
	s_mov_b32 m0, s53
	s_nop 0
	global_load_lds_dwordx4 v[212:213], off
	v_lshl_add_u64 v[212:213], v[244:245], 0, s[6:7]
	s_mov_b32 m0, s54
	s_nop 0
	global_load_lds_dwordx4 v[212:213], off
	s_waitcnt vmcnt(6)
	s_waitcnt lgkmcnt(0)
	s_barrier
	s_setprio 1
	s_waitcnt lgkmcnt(0)
	v_mfma_f32_16x16x32_bf16 v[62:65], v[144:147], v[176:179], v[62:65]
	v_mfma_f32_16x16x32_bf16 v[58:61], v[152:155], v[176:179], v[58:61]
	v_mfma_f32_16x16x32_bf16 v[46:49], v[144:147], v[184:187], v[46:49]
	v_mfma_f32_16x16x32_bf16 v[42:45], v[152:155], v[184:187], v[42:45]
	v_mfma_f32_16x16x32_bf16 v[30:33], v[144:147], v[196:199], v[30:33]
	v_mfma_f32_16x16x32_bf16 v[26:29], v[152:155], v[196:199], v[26:29]
	v_mfma_f32_16x16x32_bf16 v[14:17], v[144:147], v[204:207], v[14:17]
	v_mfma_f32_16x16x32_bf16 v[10:13], v[152:155], v[204:207], v[10:13]
	v_mfma_f32_16x16x32_bf16 v[62:65], v[148:151], v[180:183], v[62:65]
	v_mfma_f32_16x16x32_bf16 v[58:61], v[156:159], v[180:183], v[58:61]
	v_mfma_f32_16x16x32_bf16 v[46:49], v[148:151], v[192:195], v[46:49]
	v_mfma_f32_16x16x32_bf16 v[42:45], v[156:159], v[192:195], v[42:45]
	v_mfma_f32_16x16x32_bf16 v[30:33], v[148:151], v[200:203], v[30:33]
	v_mfma_f32_16x16x32_bf16 v[26:29], v[156:159], v[200:203], v[26:29]
	v_mfma_f32_16x16x32_bf16 v[14:17], v[148:151], v[208:211], v[14:17]
	v_mfma_f32_16x16x32_bf16 v[10:13], v[156:159], v[208:211], v[10:13]
	s_setprio 0
	s_setprio 1
	v_mfma_f32_16x16x32_bf16 v[54:57], v[160:163], v[176:179], v[54:57]
	v_mfma_f32_16x16x32_bf16 v[50:53], v[168:171], v[176:179], v[50:53]
	v_mfma_f32_16x16x32_bf16 v[38:41], v[160:163], v[184:187], v[38:41]
	v_mfma_f32_16x16x32_bf16 v[34:37], v[168:171], v[184:187], v[34:37]
	v_mfma_f32_16x16x32_bf16 v[22:25], v[160:163], v[196:199], v[22:25]
	v_mfma_f32_16x16x32_bf16 v[18:21], v[168:171], v[196:199], v[18:21]
	v_mfma_f32_16x16x32_bf16 v[6:9], v[160:163], v[204:207], v[6:9]
	v_mfma_f32_16x16x32_bf16 v[2:5], v[168:171], v[204:207], v[2:5]
	v_mfma_f32_16x16x32_bf16 v[54:57], v[164:167], v[180:183], v[54:57]
	v_mfma_f32_16x16x32_bf16 v[50:53], v[172:175], v[180:183], v[50:53]
	v_mfma_f32_16x16x32_bf16 v[38:41], v[164:167], v[192:195], v[38:41]
	v_mfma_f32_16x16x32_bf16 v[34:37], v[172:175], v[192:195], v[34:37]
	v_mfma_f32_16x16x32_bf16 v[22:25], v[164:167], v[200:203], v[22:25]
	v_mfma_f32_16x16x32_bf16 v[18:21], v[172:175], v[200:203], v[18:21]
	v_mfma_f32_16x16x32_bf16 v[6:9], v[164:167], v[208:211], v[6:9]
	v_mfma_f32_16x16x32_bf16 v[2:5], v[172:175], v[208:211], v[2:5]
	s_setprio 0
	s_barrier
	s_cmp_ge_i32 s58, s55
	s_mov_b64 s[46:47], s[48:49]
	s_mov_b32 s50, s58
	s_cbranch_scc0 .LBB0_131

; #define PG8_STAGE(bufoff, gbase, voff) do { _Pragma("unroll") for (int _i = 0; _i < 2; ++_i) \
;         __builtin_amdgcn_global_load_lds((const unsigned*)((const char*)(gbase) + (voff)[_i]), (LAS unsigned*)(lds + (bufoff) + ldsw + _i * 8192), 16, 0, 0); } while (0)
; #define PG8_WAIT_V(n) asm volatile("s_waitcnt vmcnt(" #n ")" ::: "memory")
; #define PG8_BAR __builtin_amdgcn_s_barrier()
; template <class Epi, class Sched>
; __device__ __forceinline__ void gemm_phase(LAS unsigned char* lds, const Gemm g, const Sched& S, const Epi& E) {
;     ...
;     PG8_STAGE(PG8_SB(1, 0), cB + kstep, voffB); PG8_STAGE(PG8_SA(1, 0), cA + kstep, voffA); PG8_STAGE(PG8_SB(1, 1), cB + hstep + kstep, voffB);
;     PG8_WAIT_V(6); PG8_BAR;
;     for (;;) {
;         const bool has_next = S.next(ui + 1, nxt);
;         const char* nA = has_next ? (const char*)g.A + (size_t)nxt.pm * tstep : cA; const char* nB = has_next ? (const char*)g.Bt + (size_t)nxt.pn * tstep : cB;
;         for (int t = 0; t < nt; t += 2) {
;     __device__ __forceinline__ void operator()(const f32x4 (&acc)[2][2][4][2], const Unit& u, int wr, int wc, int fr, int fq) const {
;         char* p = (char*)(HB + (size_t)(wr * 64 + fr) * ldc + u.pn * BM + wc * 32 + 8 * fq);
.LBB0_411:
	v_readlane_b32 s40, v249, 8
	v_readlane_b32 s41, v249, 9
	s_add_u32 s48, s46, s40
	s_addc_u32 s49, s47, s41
	v_and_b32_e32 v17, 15, v16
	s_lshr_b32 s21, s43, 26
	v_and_b32_e32 v20, 48, v16
	v_lshlrev_b32_e32 v16, 2, v16
	s_lshl_b32 s36, s36, 5
	s_add_i32 s21, s42, s21
	s_lshl_b64 s[40:41], s[42:43], 9
	v_lshl_or_b32 v18, s44, 6, v17
	v_lshl_or_b32 v17, v17, 6, v20
	s_lshl_b32 s43, s44, 13
	v_and_b32_e32 v16, 32, v16
	s_and_b32 s36, s36, 0x60
	s_add_i32 m0, s5, 0x18000
	v_lshl_add_u64 v[2:3], v[2:3], 0, s[6:7]
	s_ashr_i32 s21, s21, 6
	v_bitop3_b32 v22, v17, s43, v16 bitop3:0xde
	s_lshl_b32 s43, s36, 7
	s_waitcnt vmcnt(2)
	s_barrier
	global_load_lds_dwordx4 v[2:3], off
	s_add_i32 m0, s5, 0x1a000
	s_add_u32 s44, s1, 0xe140080
	v_mov_b32_e32 v147, v1
	v_lshl_add_u64 v[2:3], v[4:5], 0, s[6:7]
	s_addc_u32 s45, s9, 0
	s_add_i32 s54, s5, 0x8000
	v_mov_b32_e32 v145, v1
	global_load_lds_dwordx4 v[2:3], off
	v_lshl_add_u64 v[2:3], s[44:45], 0, v[146:147]
	s_mov_b32 m0, s54
	s_add_i32 s55, s5, 0xa000
	global_load_lds_dwordx4 v[2:3], off
	v_lshl_add_u64 v[2:3], s[44:45], 0, v[144:145]
	s_mov_b32 m0, s55
	v_bitop3_b32 v160, v17, s43, v16 bitop3:0xde
	global_load_lds_dwordx4 v[2:3], off
	s_add_i32 m0, s5, 0x1c000
	v_lshl_add_u64 v[2:3], v[6:7], 0, s[6:7]
	v_mov_b64_e32 v[216:217], v[6:7]
	v_lshl_add_u64 v[2:3], v[8:9], 0, s[6:7]
	s_add_i32 m0, s5, 0x1e000
	s_cmp_gt_i32 s42, 63
	v_mov_b64_e32 v[238:239], v[8:9]
	s_cselect_b64 s[42:43], -1, 0
	s_add_i32 s56, s21, -2
	v_ashrrev_i32_e32 v19, 31, v18
	s_cmpk_lt_u32 s8, 0x100
	v_lshlrev_b64 v[2:3], 11, v[18:19]
	s_cselect_b64 s[44:45], -1, 0
	v_lshl_add_u64 v[2:3], s[48:49], 0, v[2:3]
	s_lshl_b32 s36, s36, 1
	v_lshl_add_u64 v[2:3], v[2:3], 0, s[36:37]
	v_mov_b32_e32 v21, v1
	v_lshl_add_u64 v[2:3], v[2:3], 0, v[20:21]
	s_mov_b64 s[8:9], 0x6000000
	v_readlane_b32 s1, v248, 22
	v_lshl_add_u64 v[148:149], v[2:3], 0, s[8:9]
	s_add_u32 s1, s46, s1
	v_readlane_b32 s8, v248, 23
	s_addc_u32 s9, s47, s8
	v_add_u32_e32 v2, v15, v13
	s_add_u32 s8, s1, s26
	v_add_lshl_u32 v2, v2, v14, 1
	v_mov_b32_e32 v3, v1
	s_addc_u32 s9, s9, s27
	s_waitcnt vmcnt(4)
	v_lshl_add_u64 v[150:151], s[8:9], 0, v[2:3]
	v_add_u32_e32 v2, v12, v10
	v_add_lshl_u32 v2, v2, v11, 1
	v_lshl_add_u64 v[152:153], s[8:9], 0, v[2:3]
	s_mov_b32 s8, 0
	v_add_u32_e32 v161, 0, v22
	s_mov_b64 s[48:49], s[10:11]
	s_mov_b64 s[46:47], s[10:11]
	s_barrier
	s_branch .LBB0_414

; #define PG8_STAGE(bufoff, gbase, voff) do { _Pragma("unroll") for (int _i = 0; _i < 2; ++_i) \
;         __builtin_amdgcn_global_load_lds((const unsigned*)((const char*)(gbase) + (voff)[_i]), (LAS unsigned*)(lds + (bufoff) + ldsw + _i * 8192), 16, 0, 0); } while (0)
; #define PG8_LDA(dst, b, h) do { _Pragma("unroll") for (int m = 0; m < 4; ++m) _Pragma("unroll") for (int k = 0; k < 2; ++k) dst[m][k] = *(const LAS bf16x8*)(lds + PG8_SA(b, h) + aoff + m * 2048 + k * 1024); } while (0)
; #define PG8_LDB(dst, b, h) do { _Pragma("unroll") for (int n = 0; n < 2; ++n) _Pragma("unroll") for (int k = 0; k < 2; ++k) dst[n][k] = *(const LAS bf16x8*)(lds + PG8_SB(b, h) + boff + n * 2048 + k * 1024); } while (0)
; #define PG8_MMA(ai, bj, At, Bt) do { __builtin_amdgcn_s_setprio(1); _Pragma("unroll") for (int m = 0; m < 4; ++m) _Pragma("unroll") for (int n = 0; n < 2; ++n) _Pragma("unroll") for (int k = 0; k < 2; ++k) \
;         acc[ai][bj][m][n] = __builtin_amdgcn_mfma_f32_16x16x32_bf16(Bt[n][k], At[m][k], acc[ai][bj][m][n], 0, 0, 0); __builtin_amdgcn_s_setprio(0); } while (0)
; #define PG8_WAIT_V(n) asm volatile("s_waitcnt vmcnt(" #n ")" ::: "memory")
; #define PG8_WAIT_L(n) asm volatile("s_waitcnt lgkmcnt(" #n ")" ::: "memory")
; #define PG8_BAR __builtin_amdgcn_s_barrier()
; #define PG8_SCHED __builtin_amdgcn_sched_barrier(0)
; template <class Epi, class Sched>
; __device__ __forceinline__ void gemm_phase(LAS unsigned char* lds, const Gemm g, const Sched& S, const Epi& E) {
;     ...
;             PG8_LDB(B0, 0, 0); PG8_LDB(B1, 0, 1); PG8_SCHED; PG8_LDA(At, 0, 0); PG8_STAGE(PG8_SA(1, 1), a1 + hstep, voffA);
;             PG8_WAIT_V(8); PG8_WAIT_L(0); PG8_BAR; PG8_MMA(0, 0, At, B0); PG8_MMA(0, 1, At, B1); PG8_BAR; PG8_SCHED;
;             PG8_LDA(At, 0, 1); PG8_STAGE(PG8_SB(0, 0), b2, voffB); PG8_STAGE(PG8_SB(0, 1), b2 + hstep, voffB); PG8_STAGE(PG8_SA(0, 0), a2, voffA);
;             PG8_WAIT_V(8); PG8_WAIT_L(0); PG8_BAR; PG8_MMA(1, 0, At, B0); PG8_MMA(1, 1, At, B1); PG8_BAR; PG8_SCHED;
.LBB0_418:
	s_add_i32 s58, s52, 2
	s_add_u32 s50, s48, 0x100
	s_addc_u32 s51, s49, 0
	s_add_u32 s1, s9, s48
	s_addc_u32 s53, s36, s49
	s_cmp_eq_u32 s56, s52
	s_cselect_b32 s52, 0, s50
	s_cselect_b32 s59, 0, s51
	s_cselect_b32 s60, s46, s1
	s_cselect_b32 s61, s47, s53
	s_add_u32 s52, s2, s52
	s_addc_u32 s53, s3, s59
	s_add_i32 s1, 0, 0x10000
	s_add_i32 s59, 0, 0x14000
	v_add_u32_e32 v154, s1, v160
	v_add_u32_e32 v158, s59, v160
	ds_read_b128 v[130:133], v154
	ds_read_b128 v[134:137], v154 offset:1024
	ds_read_b128 v[138:141], v154 offset:2048
	ds_read_b128 v[154:157], v154 offset:3072
	ds_read_b128 v[162:165], v158
	ds_read_b128 v[166:169], v158 offset:1024
	ds_read_b128 v[170:173], v158 offset:2048
	ds_read_b128 v[174:177], v158 offset:3072
	v_lshl_add_u64 v[158:159], v[216:217], 0, s[6:7]
	s_add_i32 m0, s4, 0x1c000
	s_nop 0
	global_load_lds_dwordx4 v[158:159], off
	v_lshl_add_u64 v[158:159], v[238:239], 0, s[6:7]
	s_add_i32 m0, s4, 0x1e000
	s_nop 0
	global_load_lds_dwordx4 v[158:159], off
	v_lshl_add_u64 v[158:159], v[150:151], 0, s[48:49]
	s_add_i32 m0, s5, 0xc000
	ds_read_b128 v[178:181], v161
	ds_read_b128 v[182:185], v161 offset:1024
	ds_read_b128 v[192:195], v161 offset:2048
	ds_read_b128 v[196:199], v161 offset:3072
	ds_read_b128 v[200:203], v161 offset:4096
	ds_read_b128 v[204:207], v161 offset:5120
	ds_read_b128 v[208:211], v161 offset:6144
	ds_read_b128 v[212:215], v161 offset:7168
	global_load_lds_dwordx4 v[158:159], off
	v_lshl_add_u64 v[158:159], v[152:153], 0, s[48:49]
	s_add_i32 m0, s5, 0xe000
	s_nop 0
	global_load_lds_dwordx4 v[158:159], off
	s_waitcnt vmcnt(8)
	s_waitcnt lgkmcnt(0)
	s_barrier
	s_setprio 1
	s_waitcnt lgkmcnt(0)
	v_mfma_f32_16x16x32_bf16 v[122:125], v[130:133], v[178:181], v[122:125]
	v_mfma_f32_16x16x32_bf16 v[126:129], v[138:141], v[178:181], v[126:129]
	v_mfma_f32_16x16x32_bf16 v[110:113], v[130:133], v[192:195], v[110:113]
	v_mfma_f32_16x16x32_bf16 v[106:109], v[138:141], v[192:195], v[106:109]
	v_mfma_f32_16x16x32_bf16 v[94:97], v[130:133], v[200:203], v[94:97]
	v_mfma_f32_16x16x32_bf16 v[90:93], v[138:141], v[200:203], v[90:93]
	v_mfma_f32_16x16x32_bf16 v[78:81], v[130:133], v[208:211], v[78:81]
	v_mfma_f32_16x16x32_bf16 v[74:77], v[138:141], v[208:211], v[74:77]
	v_mfma_f32_16x16x32_bf16 v[122:125], v[134:137], v[182:185], v[122:125]
	v_mfma_f32_16x16x32_bf16 v[126:129], v[154:157], v[182:185], v[126:129]
	v_mfma_f32_16x16x32_bf16 v[110:113], v[134:137], v[196:199], v[110:113]
	v_mfma_f32_16x16x32_bf16 v[106:109], v[154:157], v[196:199], v[106:109]
	v_mfma_f32_16x16x32_bf16 v[94:97], v[134:137], v[204:207], v[94:97]
	v_mfma_f32_16x16x32_bf16 v[90:93], v[154:157], v[204:207], v[90:93]
	v_mfma_f32_16x16x32_bf16 v[78:81], v[134:137], v[212:215], v[78:81]
	v_mfma_f32_16x16x32_bf16 v[74:77], v[154:157], v[212:215], v[74:77]
	s_setprio 0
	s_setprio 1
	v_mfma_f32_16x16x32_bf16 v[118:121], v[162:165], v[178:181], v[118:121]
	v_mfma_f32_16x16x32_bf16 v[114:117], v[170:173], v[178:181], v[114:117]
	v_mfma_f32_16x16x32_bf16 v[102:105], v[162:165], v[192:195], v[102:105]
	v_mfma_f32_16x16x32_bf16 v[98:101], v[170:173], v[192:195], v[98:101]
	v_mfma_f32_16x16x32_bf16 v[86:89], v[162:165], v[200:203], v[86:89]
	v_mfma_f32_16x16x32_bf16 v[82:85], v[170:173], v[200:203], v[82:85]
	v_mfma_f32_16x16x32_bf16 v[70:73], v[162:165], v[208:211], v[70:73]
	v_mfma_f32_16x16x32_bf16 v[66:69], v[170:173], v[208:211], v[66:69]
	v_mfma_f32_16x16x32_bf16 v[118:121], v[166:169], v[182:185], v[118:121]
	v_mfma_f32_16x16x32_bf16 v[114:117], v[174:177], v[182:185], v[114:117]
	v_mfma_f32_16x16x32_bf16 v[102:105], v[166:169], v[196:199], v[102:105]
	v_mfma_f32_16x16x32_bf16 v[98:101], v[174:177], v[196:199], v[98:101]
	v_mfma_f32_16x16x32_bf16 v[86:89], v[166:169], v[204:207], v[86:89]
	v_mfma_f32_16x16x32_bf16 v[82:85], v[174:177], v[204:207], v[82:85]
	v_mfma_f32_16x16x32_bf16 v[70:73], v[166:169], v[212:215], v[70:73]
	v_mfma_f32_16x16x32_bf16 v[66:69], v[174:177], v[212:215], v[66:69]
	s_setprio 0
	s_barrier
	s_add_i32 s1, s1, s4
	v_lshl_add_u64 v[158:159], s[60:61], 0, v[0:1]
	s_mov_b32 m0, s1
	ds_read_b128 v[178:181], v161 offset:16384
	ds_read_b128 v[182:185], v161 offset:17408
	ds_read_b128 v[192:195], v161 offset:18432
	ds_read_b128 v[196:199], v161 offset:19456
	ds_read_b128 v[200:203], v161 offset:20480
	ds_read_b128 v[204:207], v161 offset:21504
	ds_read_b128 v[208:211], v161 offset:22528
	ds_read_b128 v[212:215], v161 offset:23552
	global_load_lds_dwordx4 v[158:159], off
	s_add_i32 m0, s1, 0x2000
	s_add_u32 s48, s60, s26
	v_lshl_add_u64 v[186:187], s[60:61], 0, v[142:143]
	s_addc_u32 s49, s61, s27
	s_add_i32 s1, s59, s4
	global_load_lds_dwordx4 v[186:187], off
	v_lshl_add_u64 v[216:217], s[48:49], 0, v[0:1]
	s_mov_b32 m0, s1
	v_lshl_add_u64 v[238:239], s[48:49], 0, v[142:143]
	s_add_i32 m0, s1, 0x2000
	v_lshl_add_u64 v[240:241], s[52:53], 0, v[146:147]
	s_mov_b32 m0, s5
	v_lshl_add_u64 v[244:245], s[52:53], 0, v[144:145]
	global_load_lds_dwordx4 v[240:241], off
	s_mov_b32 m0, s18
	s_nop 0
	global_load_lds_dwordx4 v[244:245], off
	s_waitcnt vmcnt(6)
	s_waitcnt lgkmcnt(0)
	s_barrier
; #define PG8_STAGE(bufoff, gbase, voff) do { _Pragma("unroll") for (int _i = 0; _i < 2; ++_i) \
;         __builtin_amdgcn_global_load_lds((const unsigned*)((const char*)(gbase) + (voff)[_i]), (LAS unsigned*)(lds + (bufoff) + ldsw + _i * 8192), 16, 0, 0); } while (0)
; #define PG8_LDA(dst, b, h) do { _Pragma("unroll") for (int m = 0; m < 4; ++m) _Pragma("unroll") for (int k = 0; k < 2; ++k) dst[m][k] = *(const LAS bf16x8*)(lds + PG8_SA(b, h) + aoff + m * 2048 + k * 1024); } while (0)
; #define PG8_LDB(dst, b, h) do { _Pragma("unroll") for (int n = 0; n < 2; ++n) _Pragma("unroll") for (int k = 0; k < 2; ++k) dst[n][k] = *(const LAS bf16x8*)(lds + PG8_SB(b, h) + boff + n * 2048 + k * 1024); } while (0)
; #define PG8_MMA(ai, bj, At, Bt) do { __builtin_amdgcn_s_setprio(1); _Pragma("unroll") for (int m = 0; m < 4; ++m) _Pragma("unroll") for (int n = 0; n < 2; ++n) _Pragma("unroll") for (int k = 0; k < 2; ++k) \
;         acc[ai][bj][m][n] = __builtin_amdgcn_mfma_f32_16x16x32_bf16(Bt[n][k], At[m][k], acc[ai][bj][m][n], 0, 0, 0); __builtin_amdgcn_s_setprio(0); } while (0)
; #define PG8_WAIT_V(n) asm volatile("s_waitcnt vmcnt(" #n ")" ::: "memory")
; #define PG8_WAIT_L(n) asm volatile("s_waitcnt lgkmcnt(" #n ")" ::: "memory")
; #define PG8_BAR __builtin_amdgcn_s_barrier()
; #define PG8_SCHED __builtin_amdgcn_sched_barrier(0)
; template <class Epi, class Sched>
; __device__ __forceinline__ void gemm_phase(LAS unsigned char* lds, const Gemm g, const Sched& S, const Epi& E) {
;     ...
;             PG8_WAIT_V(8); PG8_WAIT_L(0); PG8_BAR; PG8_MMA(1, 0, At, B0); PG8_MMA(1, 1, At, B1); PG8_BAR; PG8_SCHED;
;             PG8_LDB(B0, 1, 0); PG8_LDB(B1, 1, 1); PG8_SCHED; PG8_LDA(At, 1, 0); PG8_STAGE(PG8_SA(0, 1), a2 + hstep, voffA);
;             PG8_WAIT_V(8); PG8_WAIT_L(0); PG8_BAR; PG8_MMA(0, 0, At, B0); PG8_MMA(0, 1, At, B1); PG8_BAR; PG8_SCHED;
	s_setprio 1
	s_waitcnt lgkmcnt(0)
	v_mfma_f32_16x16x32_bf16 v[62:65], v[130:133], v[178:181], v[62:65]
	v_mfma_f32_16x16x32_bf16 v[58:61], v[138:141], v[178:181], v[58:61]
	v_mfma_f32_16x16x32_bf16 v[46:49], v[130:133], v[192:195], v[46:49]
	v_mfma_f32_16x16x32_bf16 v[42:45], v[138:141], v[192:195], v[42:45]
	v_mfma_f32_16x16x32_bf16 v[30:33], v[130:133], v[200:203], v[30:33]
	v_mfma_f32_16x16x32_bf16 v[26:29], v[138:141], v[200:203], v[26:29]
	v_mfma_f32_16x16x32_bf16 v[14:17], v[130:133], v[208:211], v[14:17]
	v_mfma_f32_16x16x32_bf16 v[10:13], v[138:141], v[208:211], v[10:13]
	v_mfma_f32_16x16x32_bf16 v[62:65], v[134:137], v[182:185], v[62:65]
	v_mfma_f32_16x16x32_bf16 v[58:61], v[154:157], v[182:185], v[58:61]
	v_mfma_f32_16x16x32_bf16 v[46:49], v[134:137], v[196:199], v[46:49]
	v_mfma_f32_16x16x32_bf16 v[42:45], v[154:157], v[196:199], v[42:45]
	v_mfma_f32_16x16x32_bf16 v[30:33], v[134:137], v[204:207], v[30:33]
	v_mfma_f32_16x16x32_bf16 v[26:29], v[154:157], v[204:207], v[26:29]
	v_mfma_f32_16x16x32_bf16 v[14:17], v[134:137], v[212:215], v[14:17]
	v_mfma_f32_16x16x32_bf16 v[10:13], v[154:157], v[212:215], v[10:13]
	s_setprio 0
	s_setprio 1
	v_mfma_f32_16x16x32_bf16 v[54:57], v[162:165], v[178:181], v[54:57]
	v_mfma_f32_16x16x32_bf16 v[50:53], v[170:173], v[178:181], v[50:53]
	v_mfma_f32_16x16x32_bf16 v[38:41], v[162:165], v[192:195], v[38:41]
	v_mfma_f32_16x16x32_bf16 v[34:37], v[170:173], v[192:195], v[34:37]
	v_mfma_f32_16x16x32_bf16 v[22:25], v[162:165], v[200:203], v[22:25]
	v_mfma_f32_16x16x32_bf16 v[18:21], v[170:173], v[200:203], v[18:21]
	v_mfma_f32_16x16x32_bf16 v[6:9], v[162:165], v[208:211], v[6:9]
	v_mfma_f32_16x16x32_bf16 v[2:5], v[170:173], v[208:211], v[2:5]
	v_mfma_f32_16x16x32_bf16 v[54:57], v[166:169], v[182:185], v[54:57]
	v_mfma_f32_16x16x32_bf16 v[50:53], v[174:177], v[182:185], v[50:53]
	v_mfma_f32_16x16x32_bf16 v[38:41], v[166:169], v[196:199], v[38:41]
	v_mfma_f32_16x16x32_bf16 v[34:37], v[174:177], v[196:199], v[34:37]
	v_mfma_f32_16x16x32_bf16 v[22:25], v[166:169], v[204:207], v[22:25]
	v_mfma_f32_16x16x32_bf16 v[18:21], v[174:177], v[204:207], v[18:21]
	v_mfma_f32_16x16x32_bf16 v[6:9], v[166:169], v[212:215], v[6:9]
	v_mfma_f32_16x16x32_bf16 v[2:5], v[174:177], v[212:215], v[2:5]
	s_setprio 0
	s_barrier
	s_add_i32 s1, 0, 0x18000
	s_add_i32 s59, 0, 0x1c000
	v_add_u32_e32 v154, s1, v160
	v_add_u32_e32 v174, s59, v160
	ds_read_b128 v[130:133], v154
	ds_read_b128 v[134:137], v154 offset:1024
	ds_read_b128 v[138:141], v154 offset:2048
	ds_read_b128 v[154:157], v154 offset:3072
	ds_read_b128 v[162:165], v174
	ds_read_b128 v[166:169], v174 offset:1024
	ds_read_b128 v[170:173], v174 offset:2048
	ds_read_b128 v[174:177], v174 offset:3072
	s_add_i32 m0, s4, 0x14000
	s_nop 0
	global_load_lds_dwordx4 v[216:217], off
	s_add_i32 m0, s4, 0x16000
	s_nop 0
	global_load_lds_dwordx4 v[238:239], off
	s_add_u32 s48, s52, s26
	s_addc_u32 s49, s53, s27
	s_mov_b32 m0, s19
	v_lshl_add_u64 v[246:247], s[48:49], 0, v[146:147]
	ds_read_b128 v[178:181], v161 offset:32768
	ds_read_b128 v[182:185], v161 offset:33792
	ds_read_b128 v[192:195], v161 offset:34816
	ds_read_b128 v[196:199], v161 offset:35840
	ds_read_b128 v[200:203], v161 offset:36864
	ds_read_b128 v[204:207], v161 offset:37888
	ds_read_b128 v[208:211], v161 offset:38912
	ds_read_b128 v[212:215], v161 offset:39936
	global_load_lds_dwordx4 v[246:247], off
	v_lshl_add_u64 v[246:247], s[48:49], 0, v[144:145]
	s_mov_b32 m0, s20
	s_nop 0
	global_load_lds_dwordx4 v[246:247], off
	s_waitcnt vmcnt(8)
	s_waitcnt lgkmcnt(0)
	s_barrier
; #define PG8_STAGE(bufoff, gbase, voff) do { _Pragma("unroll") for (int _i = 0; _i < 2; ++_i) \
;         __builtin_amdgcn_global_load_lds((const unsigned*)((const char*)(gbase) + (voff)[_i]), (LAS unsigned*)(lds + (bufoff) + ldsw + _i * 8192), 16, 0, 0); } while (0)
; #define PG8_LDA(dst, b, h) do { _Pragma("unroll") for (int m = 0; m < 4; ++m) _Pragma("unroll") for (int k = 0; k < 2; ++k) dst[m][k] = *(const LAS bf16x8*)(lds + PG8_SA(b, h) + aoff + m * 2048 + k * 1024); } while (0)
; #define PG8_MMA(ai, bj, At, Bt) do { __builtin_amdgcn_s_setprio(1); _Pragma("unroll") for (int m = 0; m < 4; ++m) _Pragma("unroll") for (int n = 0; n < 2; ++n) _Pragma("unroll") for (int k = 0; k < 2; ++k) \
;         acc[ai][bj][m][n] = __builtin_amdgcn_mfma_f32_16x16x32_bf16(Bt[n][k], At[m][k], acc[ai][bj][m][n], 0, 0, 0); __builtin_amdgcn_s_setprio(0); } while (0)
; #define PG8_WAIT_V(n) asm volatile("s_waitcnt vmcnt(" #n ")" ::: "memory")
; #define PG8_WAIT_L(n) asm volatile("s_waitcnt lgkmcnt(" #n ")" ::: "memory")
; #define PG8_BAR __builtin_amdgcn_s_barrier()
; #define PG8_SCHED __builtin_amdgcn_sched_barrier(0)
; template <class Epi, class Sched>
; __device__ __forceinline__ void gemm_phase(LAS unsigned char* lds, const Gemm g, const Sched& S, const Epi& E) {
;     ...
;             PG8_WAIT_V(8); PG8_WAIT_L(0); PG8_BAR; PG8_MMA(0, 0, At, B0); PG8_MMA(0, 1, At, B1); PG8_BAR; PG8_SCHED;
;             PG8_LDA(At, 1, 1); PG8_STAGE(PG8_SB(1, 0), b3, voffB); PG8_STAGE(PG8_SB(1, 1), b3 + hstep, voffB); PG8_STAGE(PG8_SA(1, 0), a3, voffA);
;             PG8_WAIT_V(8); PG8_WAIT_L(0); PG8_BAR; PG8_MMA(1, 0, At, B0); PG8_MMA(1, 1, At, B1); PG8_BAR; PG8_SCHED;
;         }
	s_setprio 1
	s_waitcnt lgkmcnt(0)
	v_mfma_f32_16x16x32_bf16 v[122:125], v[130:133], v[178:181], v[122:125]
	v_mfma_f32_16x16x32_bf16 v[126:129], v[138:141], v[178:181], v[126:129]
	v_mfma_f32_16x16x32_bf16 v[110:113], v[130:133], v[192:195], v[110:113]
	v_mfma_f32_16x16x32_bf16 v[106:109], v[138:141], v[192:195], v[106:109]
	v_mfma_f32_16x16x32_bf16 v[94:97], v[130:133], v[200:203], v[94:97]
	v_mfma_f32_16x16x32_bf16 v[90:93], v[138:141], v[200:203], v[90:93]
	v_mfma_f32_16x16x32_bf16 v[78:81], v[130:133], v[208:211], v[78:81]
	v_mfma_f32_16x16x32_bf16 v[74:77], v[138:141], v[208:211], v[74:77]
	v_mfma_f32_16x16x32_bf16 v[122:125], v[134:137], v[182:185], v[122:125]
	v_mfma_f32_16x16x32_bf16 v[126:129], v[154:157], v[182:185], v[126:129]
	v_mfma_f32_16x16x32_bf16 v[110:113], v[134:137], v[196:199], v[110:113]
	v_mfma_f32_16x16x32_bf16 v[106:109], v[154:157], v[196:199], v[106:109]
	v_mfma_f32_16x16x32_bf16 v[94:97], v[134:137], v[204:207], v[94:97]
	v_mfma_f32_16x16x32_bf16 v[90:93], v[154:157], v[204:207], v[90:93]
	v_mfma_f32_16x16x32_bf16 v[78:81], v[134:137], v[212:215], v[78:81]
	v_mfma_f32_16x16x32_bf16 v[74:77], v[154:157], v[212:215], v[74:77]
	s_setprio 0
	s_setprio 1
	v_mfma_f32_16x16x32_bf16 v[118:121], v[162:165], v[178:181], v[118:121]
	v_mfma_f32_16x16x32_bf16 v[114:117], v[170:173], v[178:181], v[114:117]
	v_mfma_f32_16x16x32_bf16 v[102:105], v[162:165], v[192:195], v[102:105]
	v_mfma_f32_16x16x32_bf16 v[98:101], v[170:173], v[192:195], v[98:101]
	v_mfma_f32_16x16x32_bf16 v[86:89], v[162:165], v[200:203], v[86:89]
	v_mfma_f32_16x16x32_bf16 v[82:85], v[170:173], v[200:203], v[82:85]
	v_mfma_f32_16x16x32_bf16 v[70:73], v[162:165], v[208:211], v[70:73]
	v_mfma_f32_16x16x32_bf16 v[66:69], v[170:173], v[208:211], v[66:69]
	v_mfma_f32_16x16x32_bf16 v[118:121], v[166:169], v[182:185], v[118:121]
	v_mfma_f32_16x16x32_bf16 v[114:117], v[174:177], v[182:185], v[114:117]
	v_mfma_f32_16x16x32_bf16 v[102:105], v[166:169], v[196:199], v[102:105]
	v_mfma_f32_16x16x32_bf16 v[98:101], v[174:177], v[196:199], v[98:101]
	v_mfma_f32_16x16x32_bf16 v[86:89], v[166:169], v[204:207], v[86:89]
	v_mfma_f32_16x16x32_bf16 v[82:85], v[174:177], v[204:207], v[82:85]
	v_mfma_f32_16x16x32_bf16 v[70:73], v[166:169], v[212:215], v[70:73]
	v_mfma_f32_16x16x32_bf16 v[66:69], v[174:177], v[212:215], v[66:69]
	s_setprio 0
	s_barrier
	s_add_i32 s1, s1, s4
	v_lshl_add_u64 v[158:159], v[158:159], 0, s[6:7]
	s_mov_b32 m0, s1
	ds_read_b128 v[178:181], v161 offset:49152
	ds_read_b128 v[182:185], v161 offset:50176
	ds_read_b128 v[192:195], v161 offset:51200
	ds_read_b128 v[196:199], v161 offset:52224
	ds_read_b128 v[200:203], v161 offset:53248
	ds_read_b128 v[204:207], v161 offset:54272
	ds_read_b128 v[208:211], v161 offset:55296
	ds_read_b128 v[212:215], v161 offset:56320
	global_load_lds_dwordx4 v[158:159], off
	v_lshl_add_u64 v[158:159], v[186:187], 0, s[6:7]
	s_add_i32 m0, s1, 0x2000
	s_add_i32 s1, s59, s4
	global_load_lds_dwordx4 v[158:159], off
	v_lshl_add_u64 v[158:159], v[216:217], 0, s[6:7]
	s_mov_b32 m0, s1
	s_nop 0
	v_lshl_add_u64 v[158:159], v[238:239], 0, s[6:7]
	s_add_i32 m0, s1, 0x2000
	s_nop 0
	v_lshl_add_u64 v[158:159], v[240:241], 0, s[6:7]
	s_mov_b32 m0, s54
	s_nop 0
	global_load_lds_dwordx4 v[158:159], off
	v_lshl_add_u64 v[158:159], v[244:245], 0, s[6:7]
	s_mov_b32 m0, s55
	s_nop 0
	global_load_lds_dwordx4 v[158:159], off
	s_waitcnt vmcnt(6)
	s_waitcnt lgkmcnt(0)
	s_barrier
	s_setprio 1
	s_waitcnt lgkmcnt(0)
	v_mfma_f32_16x16x32_bf16 v[62:65], v[130:133], v[178:181], v[62:65]
	v_mfma_f32_16x16x32_bf16 v[58:61], v[138:141], v[178:181], v[58:61]
	v_mfma_f32_16x16x32_bf16 v[46:49], v[130:133], v[192:195], v[46:49]
	v_mfma_f32_16x16x32_bf16 v[42:45], v[138:141], v[192:195], v[42:45]
	v_mfma_f32_16x16x32_bf16 v[30:33], v[130:133], v[200:203], v[30:33]
	v_mfma_f32_16x16x32_bf16 v[26:29], v[138:141], v[200:203], v[26:29]
	v_mfma_f32_16x16x32_bf16 v[14:17], v[130:133], v[208:211], v[14:17]
	v_mfma_f32_16x16x32_bf16 v[10:13], v[138:141], v[208:211], v[10:13]
	v_mfma_f32_16x16x32_bf16 v[62:65], v[134:137], v[182:185], v[62:65]
	v_mfma_f32_16x16x32_bf16 v[58:61], v[154:157], v[182:185], v[58:61]
	v_mfma_f32_16x16x32_bf16 v[46:49], v[134:137], v[196:199], v[46:49]
	v_mfma_f32_16x16x32_bf16 v[42:45], v[154:157], v[196:199], v[42:45]
	v_mfma_f32_16x16x32_bf16 v[30:33], v[134:137], v[204:207], v[30:33]
	v_mfma_f32_16x16x32_bf16 v[26:29], v[154:157], v[204:207], v[26:29]
	v_mfma_f32_16x16x32_bf16 v[14:17], v[134:137], v[212:215], v[14:17]
	v_mfma_f32_16x16x32_bf16 v[10:13], v[154:157], v[212:215], v[10:13]
	s_setprio 0
	s_setprio 1
	v_mfma_f32_16x16x32_bf16 v[54:57], v[162:165], v[178:181], v[54:57]
	v_mfma_f32_16x16x32_bf16 v[50:53], v[170:173], v[178:181], v[50:53]
	v_mfma_f32_16x16x32_bf16 v[38:41], v[162:165], v[192:195], v[38:41]
	v_mfma_f32_16x16x32_bf16 v[34:37], v[170:173], v[192:195], v[34:37]
	v_mfma_f32_16x16x32_bf16 v[22:25], v[162:165], v[200:203], v[22:25]
	v_mfma_f32_16x16x32_bf16 v[18:21], v[170:173], v[200:203], v[18:21]
	v_mfma_f32_16x16x32_bf16 v[6:9], v[162:165], v[208:211], v[6:9]
	v_mfma_f32_16x16x32_bf16 v[2:5], v[170:173], v[208:211], v[2:5]
	v_mfma_f32_16x16x32_bf16 v[54:57], v[166:169], v[182:185], v[54:57]
	v_mfma_f32_16x16x32_bf16 v[50:53], v[174:177], v[182:185], v[50:53]
	v_mfma_f32_16x16x32_bf16 v[38:41], v[166:169], v[196:199], v[38:41]
	v_mfma_f32_16x16x32_bf16 v[34:37], v[174:177], v[196:199], v[34:37]
	v_mfma_f32_16x16x32_bf16 v[22:25], v[166:169], v[204:207], v[22:25]
	v_mfma_f32_16x16x32_bf16 v[18:21], v[174:177], v[204:207], v[18:21]
	v_mfma_f32_16x16x32_bf16 v[6:9], v[166:169], v[212:215], v[6:9]
	v_mfma_f32_16x16x32_bf16 v[2:5], v[174:177], v[212:215], v[2:5]
	s_setprio 0
	s_barrier
	s_cmp_ge_i32 s58, s21
	s_mov_b64 s[48:49], s[50:51]
	s_mov_b32 s52, s58
	s_cbranch_scc0 .LBB0_418

; #define PG8_STAGE(bufoff, gbase, voff) do { _Pragma("unroll") for (int _i = 0; _i < 2; ++_i) \
;         __builtin_amdgcn_global_load_lds((const unsigned*)((const char*)(gbase) + (voff)[_i]), (LAS unsigned*)(lds + (bufoff) + ldsw + _i * 8192), 16, 0, 0); } while (0)
; #define PG8_WAIT_V(n) asm volatile("s_waitcnt vmcnt(" #n ")" ::: "memory")
; #define PG8_BAR __builtin_amdgcn_s_barrier()
; template <class Epi, class Sched>
; __device__ __forceinline__ void gemm_phase(LAS unsigned char* lds, const Gemm g, const Sched& S, const Epi& E) {
;     ...
;     PG8_STAGE(PG8_SB(1, 0), cB + kstep, voffB); PG8_STAGE(PG8_SA(1, 0), cA + kstep, voffA); PG8_STAGE(PG8_SB(1, 1), cB + hstep + kstep, voffB);
;     PG8_WAIT_V(6); PG8_BAR;
;     for (;;) {
;         const bool has_next = S.next(ui + 1, nxt);
;         const char* nA = has_next ? (const char*)g.A + (size_t)nxt.pm * tstep : cA; const char* nB = has_next ? (const char*)g.Bt + (size_t)nxt.pn * tstep : cB;
;         for (int t = 0; t < nt; t += 2) {
;     __device__ __forceinline__ void operator()(const f32x4 (&acc)[2][2][4][2], const Unit& u, int wr, int wc, int fr, int fq) const {
;         char* p = (char*)(O + (size_t)(wr * 64 + fr) * ldc + u.pn * BM + wc * 32 + 8 * fq);
.LBB0_428:
	s_add_u32 s48, s46, s88
	s_addc_u32 s49, s47, s89
	s_add_i32 m0, s5, 0x18000
	v_lshl_add_u64 v[2:3], v[2:3], 0, s[6:7]
	s_waitcnt vmcnt(2)
	s_barrier
	global_load_lds_dwordx4 v[2:3], off
	v_lshl_add_u64 v[2:3], v[4:5], 0, s[6:7]
	s_add_i32 m0, s5, 0x1a000
	s_add_i32 s57, s5, 0x8000
	global_load_lds_dwordx4 v[2:3], off
	v_lshl_add_u64 v[2:3], v[10:11], 0, s[6:7]
	s_mov_b32 m0, s57
	s_add_i32 s58, s5, 0xa000
	global_load_lds_dwordx4 v[2:3], off
	v_lshl_add_u64 v[2:3], v[12:13], 0, s[6:7]
	s_mov_b32 m0, s58
	s_lshr_b32 s1, s43, 26
	global_load_lds_dwordx4 v[2:3], off
	s_add_i32 m0, s5, 0x1c000
	v_lshl_add_u64 v[2:3], v[6:7], 0, s[6:7]
	v_mov_b64_e32 v[216:217], v[6:7]
	v_lshl_add_u64 v[2:3], v[8:9], 0, s[6:7]
	s_add_i32 m0, s5, 0x1e000
	s_add_i32 s1, s42, s1
	v_mov_b64_e32 v[238:239], v[8:9]
	v_and_b32_e32 v3, 15, v15
	v_and_b32_e32 v4, 48, v15
	v_lshlrev_b32_e32 v5, 2, v15
	s_ashr_i32 s59, s1, 6
	v_lshl_or_b32 v2, s36, 6, v3
	v_lshl_or_b32 v3, v3, 6, v4
	s_lshl_b32 s1, s36, 13
	v_and_b32_e32 v5, 32, v5
	v_bitop3_b32 v6, v3, s1, v5 bitop3:0xde
	s_lshl_b32 s1, s9, 5
	s_and_b32 s1, s1, 0x60
	s_lshl_b64 s[40:41], s[42:43], 9
	s_lshl_b32 s9, s1, 7
	s_cmp_gt_i32 s42, 63
	v_bitop3_b32 v142, v3, s9, v5 bitop3:0xde
	s_cselect_b64 s[42:43], -1, 0
	s_add_i32 s60, s59, -2
	v_ashrrev_i32_e32 v3, 31, v2
	s_cmpk_lt_u32 s8, 0x100
	v_lshlrev_b64 v[2:3], 13, v[2:3]
	s_cselect_b64 s[44:45], -1, 0
	v_lshl_add_u64 v[2:3], s[48:49], 0, v[2:3]
	s_lshl_b32 s36, s1, 1
	v_lshl_add_u64 v[2:3], v[2:3], 0, s[36:37]
	v_mov_b32_e32 v5, v1
	v_lshl_add_u64 v[2:3], v[2:3], 0, v[4:5]
	s_mov_b64 s[8:9], 0xe000000
	v_readlane_b32 s1, v248, 14
	v_lshl_add_u64 v[136:137], v[2:3], 0, s[8:9]
	s_add_u32 s1, s46, s1
	v_readlane_b32 s8, v248, 15
	s_addc_u32 s9, s47, s8
	v_add_u32_e32 v2, v20, v18
	s_add_u32 s8, s1, s26
	v_add_lshl_u32 v2, v2, v19, 1
	v_mov_b32_e32 v3, v1
	s_addc_u32 s9, s9, s27
	s_waitcnt vmcnt(4)
	v_lshl_add_u64 v[138:139], s[8:9], 0, v[2:3]
	v_add_u32_e32 v2, v17, v14
	v_add_lshl_u32 v2, v2, v16, 1
	v_lshl_add_u64 v[140:141], s[8:9], 0, v[2:3]
	s_mov_b32 s8, 0
	v_add_u32_e32 v143, 0, v6
	s_mov_b64 s[48:49], s[18:19]
	s_mov_b64 s[46:47], s[18:19]
	s_barrier
	s_branch .LBB0_431

; #define PG8_STAGE(bufoff, gbase, voff) do { _Pragma("unroll") for (int _i = 0; _i < 2; ++_i) \
;         __builtin_amdgcn_global_load_lds((const unsigned*)((const char*)(gbase) + (voff)[_i]), (LAS unsigned*)(lds + (bufoff) + ldsw + _i * 8192), 16, 0, 0); } while (0)
; #define PG8_LDA(dst, b, h) do { _Pragma("unroll") for (int m = 0; m < 4; ++m) _Pragma("unroll") for (int k = 0; k < 2; ++k) dst[m][k] = *(const LAS bf16x8*)(lds + PG8_SA(b, h) + aoff + m * 2048 + k * 1024); } while (0)
; #define PG8_LDB(dst, b, h) do { _Pragma("unroll") for (int n = 0; n < 2; ++n) _Pragma("unroll") for (int k = 0; k < 2; ++k) dst[n][k] = *(const LAS bf16x8*)(lds + PG8_SB(b, h) + boff + n * 2048 + k * 1024); } while (0)
; #define PG8_MMA(ai, bj, At, Bt) do { __builtin_amdgcn_s_setprio(1); _Pragma("unroll") for (int m = 0; m < 4; ++m) _Pragma("unroll") for (int n = 0; n < 2; ++n) _Pragma("unroll") for (int k = 0; k < 2; ++k) \
;         acc[ai][bj][m][n] = __builtin_amdgcn_mfma_f32_16x16x32_bf16(Bt[n][k], At[m][k], acc[ai][bj][m][n], 0, 0, 0); __builtin_amdgcn_s_setprio(0); } while (0)
; #define PG8_WAIT_V(n) asm volatile("s_waitcnt vmcnt(" #n ")" ::: "memory")
; #define PG8_WAIT_L(n) asm volatile("s_waitcnt lgkmcnt(" #n ")" ::: "memory")
; #define PG8_BAR __builtin_amdgcn_s_barrier()
; #define PG8_SCHED __builtin_amdgcn_sched_barrier(0)
; template <class Epi, class Sched>
; __device__ __forceinline__ void gemm_phase(LAS unsigned char* lds, const Gemm g, const Sched& S, const Epi& E) {
;     ...
;             PG8_LDB(B0, 0, 0); PG8_LDB(B1, 0, 1); PG8_SCHED; PG8_LDA(At, 0, 0); PG8_STAGE(PG8_SA(1, 1), a1 + hstep, voffA);
;             PG8_WAIT_V(8); PG8_WAIT_L(0); PG8_BAR; PG8_MMA(0, 0, At, B0); PG8_MMA(0, 1, At, B1); PG8_BAR; PG8_SCHED;
;             PG8_LDA(At, 0, 1); PG8_STAGE(PG8_SB(0, 0), b2, voffB); PG8_STAGE(PG8_SB(0, 1), b2 + hstep, voffB); PG8_STAGE(PG8_SA(0, 0), a2, voffA);
;             PG8_WAIT_V(8); PG8_WAIT_L(0); PG8_BAR; PG8_MMA(1, 0, At, B0); PG8_MMA(1, 1, At, B1); PG8_BAR; PG8_SCHED;
.LBB0_435:
	s_add_i32 s62, s52, 2
	s_add_u32 s50, s48, 0x100
	s_addc_u32 s51, s49, 0
	s_add_u32 s1, s9, s48
	s_addc_u32 s53, s36, s49
	s_cmp_eq_u32 s60, s52
	s_cselect_b32 s52, 0, s50
	s_cselect_b32 s63, 0, s51
	s_cselect_b32 s64, s46, s1
	s_cselect_b32 s65, s47, s53
	s_add_u32 s52, s2, s52
	s_addc_u32 s53, s3, s63
	s_add_i32 s1, 0, 0x10000
	s_add_i32 s63, 0, 0x14000
	v_add_u32_e32 v156, s1, v142
	v_add_u32_e32 v172, s63, v142
	ds_read_b128 v[144:147], v156
	ds_read_b128 v[148:151], v156 offset:1024
	ds_read_b128 v[152:155], v156 offset:2048
	ds_read_b128 v[156:159], v156 offset:3072
	ds_read_b128 v[160:163], v172
	ds_read_b128 v[164:167], v172 offset:1024
	ds_read_b128 v[168:171], v172 offset:2048
	ds_read_b128 v[172:175], v172 offset:3072
	v_lshl_add_u64 v[212:213], v[216:217], 0, s[6:7]
	s_add_i32 m0, s4, 0x1c000
	s_nop 0
	global_load_lds_dwordx4 v[212:213], off
	v_lshl_add_u64 v[212:213], v[238:239], 0, s[6:7]
	s_add_i32 m0, s4, 0x1e000
	s_nop 0
	global_load_lds_dwordx4 v[212:213], off
	v_lshl_add_u64 v[212:213], v[138:139], 0, s[48:49]
	s_add_i32 m0, s5, 0xc000
	ds_read_b128 v[176:179], v143
	ds_read_b128 v[180:183], v143 offset:1024
	ds_read_b128 v[184:187], v143 offset:2048
	ds_read_b128 v[192:195], v143 offset:3072
	ds_read_b128 v[196:199], v143 offset:4096
	ds_read_b128 v[200:203], v143 offset:5120
	ds_read_b128 v[204:207], v143 offset:6144
	ds_read_b128 v[208:211], v143 offset:7168
	global_load_lds_dwordx4 v[212:213], off
	v_lshl_add_u64 v[212:213], v[140:141], 0, s[48:49]
	s_add_i32 m0, s5, 0xe000
	s_nop 0
	global_load_lds_dwordx4 v[212:213], off
	s_waitcnt vmcnt(8)
	s_waitcnt lgkmcnt(0)
	s_barrier
	s_setprio 1
	s_waitcnt lgkmcnt(0)
	v_mfma_f32_16x16x32_bf16 v[122:125], v[144:147], v[176:179], v[122:125]
	v_mfma_f32_16x16x32_bf16 v[126:129], v[152:155], v[176:179], v[126:129]
	v_mfma_f32_16x16x32_bf16 v[110:113], v[144:147], v[184:187], v[110:113]
	v_mfma_f32_16x16x32_bf16 v[106:109], v[152:155], v[184:187], v[106:109]
	v_mfma_f32_16x16x32_bf16 v[94:97], v[144:147], v[196:199], v[94:97]
	v_mfma_f32_16x16x32_bf16 v[90:93], v[152:155], v[196:199], v[90:93]
	v_mfma_f32_16x16x32_bf16 v[78:81], v[144:147], v[204:207], v[78:81]
	v_mfma_f32_16x16x32_bf16 v[74:77], v[152:155], v[204:207], v[74:77]
	v_mfma_f32_16x16x32_bf16 v[122:125], v[148:151], v[180:183], v[122:125]
	v_mfma_f32_16x16x32_bf16 v[126:129], v[156:159], v[180:183], v[126:129]
	v_mfma_f32_16x16x32_bf16 v[110:113], v[148:151], v[192:195], v[110:113]
	v_mfma_f32_16x16x32_bf16 v[106:109], v[156:159], v[192:195], v[106:109]
	v_mfma_f32_16x16x32_bf16 v[94:97], v[148:151], v[200:203], v[94:97]
	v_mfma_f32_16x16x32_bf16 v[90:93], v[156:159], v[200:203], v[90:93]
	v_mfma_f32_16x16x32_bf16 v[78:81], v[148:151], v[208:211], v[78:81]
	v_mfma_f32_16x16x32_bf16 v[74:77], v[156:159], v[208:211], v[74:77]
	s_setprio 0
	s_setprio 1
	v_mfma_f32_16x16x32_bf16 v[118:121], v[160:163], v[176:179], v[118:121]
	v_mfma_f32_16x16x32_bf16 v[114:117], v[168:171], v[176:179], v[114:117]
	v_mfma_f32_16x16x32_bf16 v[102:105], v[160:163], v[184:187], v[102:105]
	v_mfma_f32_16x16x32_bf16 v[98:101], v[168:171], v[184:187], v[98:101]
	v_mfma_f32_16x16x32_bf16 v[86:89], v[160:163], v[196:199], v[86:89]
	v_mfma_f32_16x16x32_bf16 v[82:85], v[168:171], v[196:199], v[82:85]
	v_mfma_f32_16x16x32_bf16 v[70:73], v[160:163], v[204:207], v[70:73]
	v_mfma_f32_16x16x32_bf16 v[66:69], v[168:171], v[204:207], v[66:69]
	v_mfma_f32_16x16x32_bf16 v[118:121], v[164:167], v[180:183], v[118:121]
	v_mfma_f32_16x16x32_bf16 v[114:117], v[172:175], v[180:183], v[114:117]
	v_mfma_f32_16x16x32_bf16 v[102:105], v[164:167], v[192:195], v[102:105]
	v_mfma_f32_16x16x32_bf16 v[98:101], v[172:175], v[192:195], v[98:101]
	v_mfma_f32_16x16x32_bf16 v[86:89], v[164:167], v[200:203], v[86:89]
	v_mfma_f32_16x16x32_bf16 v[82:85], v[172:175], v[200:203], v[82:85]
	v_mfma_f32_16x16x32_bf16 v[70:73], v[164:167], v[208:211], v[70:73]
	v_mfma_f32_16x16x32_bf16 v[66:69], v[172:175], v[208:211], v[66:69]
	s_setprio 0
	s_barrier
	s_add_i32 s1, s1, s4
	v_lshl_add_u64 v[212:213], s[64:65], 0, v[0:1]
	s_mov_b32 m0, s1
	ds_read_b128 v[176:179], v143 offset:16384
	ds_read_b128 v[180:183], v143 offset:17408
	ds_read_b128 v[184:187], v143 offset:18432
	ds_read_b128 v[192:195], v143 offset:19456
	ds_read_b128 v[196:199], v143 offset:20480
	ds_read_b128 v[200:203], v143 offset:21504
	ds_read_b128 v[204:207], v143 offset:22528
	ds_read_b128 v[208:211], v143 offset:23552
	global_load_lds_dwordx4 v[212:213], off
	s_add_i32 m0, s1, 0x2000
	s_add_u32 s48, s64, s26
	v_lshl_add_u64 v[214:215], s[64:65], 0, v[130:131]
	s_addc_u32 s49, s65, s27
	s_add_i32 s1, s63, s4
	global_load_lds_dwordx4 v[214:215], off
	v_lshl_add_u64 v[216:217], s[48:49], 0, v[0:1]
	s_mov_b32 m0, s1
	v_lshl_add_u64 v[238:239], s[48:49], 0, v[130:131]
	s_add_i32 m0, s1, 0x2000
	v_lshl_add_u64 v[240:241], s[52:53], 0, v[134:135]
	s_mov_b32 m0, s5
	v_lshl_add_u64 v[244:245], s[52:53], 0, v[132:133]
	global_load_lds_dwordx4 v[240:241], off
	s_mov_b32 m0, s54
	s_nop 0
	global_load_lds_dwordx4 v[244:245], off
	s_waitcnt vmcnt(6)
	s_waitcnt lgkmcnt(0)
	s_barrier
; #define PG8_STAGE(bufoff, gbase, voff) do { _Pragma("unroll") for (int _i = 0; _i < 2; ++_i) \
;         __builtin_amdgcn_global_load_lds((const unsigned*)((const char*)(gbase) + (voff)[_i]), (LAS unsigned*)(lds + (bufoff) + ldsw + _i * 8192), 16, 0, 0); } while (0)
; #define PG8_LDA(dst, b, h) do { _Pragma("unroll") for (int m = 0; m < 4; ++m) _Pragma("unroll") for (int k = 0; k < 2; ++k) dst[m][k] = *(const LAS bf16x8*)(lds + PG8_SA(b, h) + aoff + m * 2048 + k * 1024); } while (0)
; #define PG8_LDB(dst, b, h) do { _Pragma("unroll") for (int n = 0; n < 2; ++n) _Pragma("unroll") for (int k = 0; k < 2; ++k) dst[n][k] = *(const LAS bf16x8*)(lds + PG8_SB(b, h) + boff + n * 2048 + k * 1024); } while (0)
; #define PG8_MMA(ai, bj, At, Bt) do { __builtin_amdgcn_s_setprio(1); _Pragma("unroll") for (int m = 0; m < 4; ++m) _Pragma("unroll") for (int n = 0; n < 2; ++n) _Pragma("unroll") for (int k = 0; k < 2; ++k) \
;         acc[ai][bj][m][n] = __builtin_amdgcn_mfma_f32_16x16x32_bf16(Bt[n][k], At[m][k], acc[ai][bj][m][n], 0, 0, 0); __builtin_amdgcn_s_setprio(0); } while (0)
; #define PG8_WAIT_V(n) asm volatile("s_waitcnt vmcnt(" #n ")" ::: "memory")
; #define PG8_WAIT_L(n) asm volatile("s_waitcnt lgkmcnt(" #n ")" ::: "memory")
; #define PG8_BAR __builtin_amdgcn_s_barrier()
; #define PG8_SCHED __builtin_amdgcn_sched_barrier(0)
; template <class Epi, class Sched>
; __device__ __forceinline__ void gemm_phase(LAS unsigned char* lds, const Gemm g, const Sched& S, const Epi& E) {
;     ...
;             PG8_WAIT_V(8); PG8_WAIT_L(0); PG8_BAR; PG8_MMA(1, 0, At, B0); PG8_MMA(1, 1, At, B1); PG8_BAR; PG8_SCHED;
;             PG8_LDB(B0, 1, 0); PG8_LDB(B1, 1, 1); PG8_SCHED; PG8_LDA(At, 1, 0); PG8_STAGE(PG8_SA(0, 1), a2 + hstep, voffA);
;             PG8_WAIT_V(8); PG8_WAIT_L(0); PG8_BAR; PG8_MMA(0, 0, At, B0); PG8_MMA(0, 1, At, B1); PG8_BAR; PG8_SCHED;
	s_setprio 1
	s_waitcnt lgkmcnt(0)
	v_mfma_f32_16x16x32_bf16 v[62:65], v[144:147], v[176:179], v[62:65]
	v_mfma_f32_16x16x32_bf16 v[58:61], v[152:155], v[176:179], v[58:61]
	v_mfma_f32_16x16x32_bf16 v[46:49], v[144:147], v[184:187], v[46:49]
	v_mfma_f32_16x16x32_bf16 v[42:45], v[152:155], v[184:187], v[42:45]
	v_mfma_f32_16x16x32_bf16 v[30:33], v[144:147], v[196:199], v[30:33]
	v_mfma_f32_16x16x32_bf16 v[26:29], v[152:155], v[196:199], v[26:29]
	v_mfma_f32_16x16x32_bf16 v[14:17], v[144:147], v[204:207], v[14:17]
	v_mfma_f32_16x16x32_bf16 v[10:13], v[152:155], v[204:207], v[10:13]
	v_mfma_f32_16x16x32_bf16 v[62:65], v[148:151], v[180:183], v[62:65]
	v_mfma_f32_16x16x32_bf16 v[58:61], v[156:159], v[180:183], v[58:61]
	v_mfma_f32_16x16x32_bf16 v[46:49], v[148:151], v[192:195], v[46:49]
	v_mfma_f32_16x16x32_bf16 v[42:45], v[156:159], v[192:195], v[42:45]
	v_mfma_f32_16x16x32_bf16 v[30:33], v[148:151], v[200:203], v[30:33]
	v_mfma_f32_16x16x32_bf16 v[26:29], v[156:159], v[200:203], v[26:29]
	v_mfma_f32_16x16x32_bf16 v[14:17], v[148:151], v[208:211], v[14:17]
	v_mfma_f32_16x16x32_bf16 v[10:13], v[156:159], v[208:211], v[10:13]
	s_setprio 0
	s_setprio 1
	v_mfma_f32_16x16x32_bf16 v[54:57], v[160:163], v[176:179], v[54:57]
	v_mfma_f32_16x16x32_bf16 v[50:53], v[168:171], v[176:179], v[50:53]
	v_mfma_f32_16x16x32_bf16 v[38:41], v[160:163], v[184:187], v[38:41]
	v_mfma_f32_16x16x32_bf16 v[34:37], v[168:171], v[184:187], v[34:37]
	v_mfma_f32_16x16x32_bf16 v[22:25], v[160:163], v[196:199], v[22:25]
	v_mfma_f32_16x16x32_bf16 v[18:21], v[168:171], v[196:199], v[18:21]
	v_mfma_f32_16x16x32_bf16 v[6:9], v[160:163], v[204:207], v[6:9]
	v_mfma_f32_16x16x32_bf16 v[2:5], v[168:171], v[204:207], v[2:5]
	v_mfma_f32_16x16x32_bf16 v[54:57], v[164:167], v[180:183], v[54:57]
	v_mfma_f32_16x16x32_bf16 v[50:53], v[172:175], v[180:183], v[50:53]
	v_mfma_f32_16x16x32_bf16 v[38:41], v[164:167], v[192:195], v[38:41]
	v_mfma_f32_16x16x32_bf16 v[34:37], v[172:175], v[192:195], v[34:37]
	v_mfma_f32_16x16x32_bf16 v[22:25], v[164:167], v[200:203], v[22:25]
	v_mfma_f32_16x16x32_bf16 v[18:21], v[172:175], v[200:203], v[18:21]
	v_mfma_f32_16x16x32_bf16 v[6:9], v[164:167], v[208:211], v[6:9]
	v_mfma_f32_16x16x32_bf16 v[2:5], v[172:175], v[208:211], v[2:5]
	s_setprio 0
	s_barrier
	s_add_i32 s1, 0, 0x18000
	s_add_i32 s63, 0, 0x1c000
	v_add_u32_e32 v156, s1, v142
	v_add_u32_e32 v172, s63, v142
	ds_read_b128 v[144:147], v156
	ds_read_b128 v[148:151], v156 offset:1024
	ds_read_b128 v[152:155], v156 offset:2048
	ds_read_b128 v[156:159], v156 offset:3072
	ds_read_b128 v[160:163], v172
	ds_read_b128 v[164:167], v172 offset:1024
	ds_read_b128 v[168:171], v172 offset:2048
	ds_read_b128 v[172:175], v172 offset:3072
	s_add_i32 m0, s4, 0x14000
	s_nop 0
	global_load_lds_dwordx4 v[216:217], off
	s_add_i32 m0, s4, 0x16000
	s_nop 0
	global_load_lds_dwordx4 v[238:239], off
	s_add_u32 s48, s52, s26
	s_addc_u32 s49, s53, s27
	s_mov_b32 m0, s55
	v_lshl_add_u64 v[246:247], s[48:49], 0, v[134:135]
	ds_read_b128 v[176:179], v143 offset:32768
	ds_read_b128 v[180:183], v143 offset:33792
	ds_read_b128 v[184:187], v143 offset:34816
	ds_read_b128 v[192:195], v143 offset:35840
	ds_read_b128 v[196:199], v143 offset:36864
	ds_read_b128 v[200:203], v143 offset:37888
	ds_read_b128 v[204:207], v143 offset:38912
	ds_read_b128 v[208:211], v143 offset:39936
	global_load_lds_dwordx4 v[246:247], off
	v_lshl_add_u64 v[246:247], s[48:49], 0, v[132:133]
	s_mov_b32 m0, s56
	s_nop 0
	global_load_lds_dwordx4 v[246:247], off
	s_waitcnt vmcnt(8)
	s_waitcnt lgkmcnt(0)
	s_barrier
; #define PG8_STAGE(bufoff, gbase, voff) do { _Pragma("unroll") for (int _i = 0; _i < 2; ++_i) \
;         __builtin_amdgcn_global_load_lds((const unsigned*)((const char*)(gbase) + (voff)[_i]), (LAS unsigned*)(lds + (bufoff) + ldsw + _i * 8192), 16, 0, 0); } while (0)
; #define PG8_LDA(dst, b, h) do { _Pragma("unroll") for (int m = 0; m < 4; ++m) _Pragma("unroll") for (int k = 0; k < 2; ++k) dst[m][k] = *(const LAS bf16x8*)(lds + PG8_SA(b, h) + aoff + m * 2048 + k * 1024); } while (0)
; #define PG8_MMA(ai, bj, At, Bt) do { __builtin_amdgcn_s_setprio(1); _Pragma("unroll") for (int m = 0; m < 4; ++m) _Pragma("unroll") for (int n = 0; n < 2; ++n) _Pragma("unroll") for (int k = 0; k < 2; ++k) \
;         acc[ai][bj][m][n] = __builtin_amdgcn_mfma_f32_16x16x32_bf16(Bt[n][k], At[m][k], acc[ai][bj][m][n], 0, 0, 0); __builtin_amdgcn_s_setprio(0); } while (0)
; #define PG8_WAIT_V(n) asm volatile("s_waitcnt vmcnt(" #n ")" ::: "memory")
; #define PG8_WAIT_L(n) asm volatile("s_waitcnt lgkmcnt(" #n ")" ::: "memory")
; #define PG8_BAR __builtin_amdgcn_s_barrier()
; #define PG8_SCHED __builtin_amdgcn_sched_barrier(0)
; template <class Epi, class Sched>
; __device__ __forceinline__ void gemm_phase(LAS unsigned char* lds, const Gemm g, const Sched& S, const Epi& E) {
;     ...
;             PG8_WAIT_V(8); PG8_WAIT_L(0); PG8_BAR; PG8_MMA(0, 0, At, B0); PG8_MMA(0, 1, At, B1); PG8_BAR; PG8_SCHED;
;             PG8_LDA(At, 1, 1); PG8_STAGE(PG8_SB(1, 0), b3, voffB); PG8_STAGE(PG8_SB(1, 1), b3 + hstep, voffB); PG8_STAGE(PG8_SA(1, 0), a3, voffA);
;             PG8_WAIT_V(8); PG8_WAIT_L(0); PG8_BAR; PG8_MMA(1, 0, At, B0); PG8_MMA(1, 1, At, B1); PG8_BAR; PG8_SCHED;
;         }
	s_setprio 1
	s_waitcnt lgkmcnt(0)
	v_mfma_f32_16x16x32_bf16 v[122:125], v[144:147], v[176:179], v[122:125]
	v_mfma_f32_16x16x32_bf16 v[126:129], v[152:155], v[176:179], v[126:129]
	v_mfma_f32_16x16x32_bf16 v[110:113], v[144:147], v[184:187], v[110:113]
	v_mfma_f32_16x16x32_bf16 v[106:109], v[152:155], v[184:187], v[106:109]
	v_mfma_f32_16x16x32_bf16 v[94:97], v[144:147], v[196:199], v[94:97]
	v_mfma_f32_16x16x32_bf16 v[90:93], v[152:155], v[196:199], v[90:93]
	v_mfma_f32_16x16x32_bf16 v[78:81], v[144:147], v[204:207], v[78:81]
	v_mfma_f32_16x16x32_bf16 v[74:77], v[152:155], v[204:207], v[74:77]
	v_mfma_f32_16x16x32_bf16 v[122:125], v[148:151], v[180:183], v[122:125]
	v_mfma_f32_16x16x32_bf16 v[126:129], v[156:159], v[180:183], v[126:129]
	v_mfma_f32_16x16x32_bf16 v[110:113], v[148:151], v[192:195], v[110:113]
	v_mfma_f32_16x16x32_bf16 v[106:109], v[156:159], v[192:195], v[106:109]
	v_mfma_f32_16x16x32_bf16 v[94:97], v[148:151], v[200:203], v[94:97]
	v_mfma_f32_16x16x32_bf16 v[90:93], v[156:159], v[200:203], v[90:93]
	v_mfma_f32_16x16x32_bf16 v[78:81], v[148:151], v[208:211], v[78:81]
	v_mfma_f32_16x16x32_bf16 v[74:77], v[156:159], v[208:211], v[74:77]
	s_setprio 0
	s_setprio 1
	v_mfma_f32_16x16x32_bf16 v[118:121], v[160:163], v[176:179], v[118:121]
	v_mfma_f32_16x16x32_bf16 v[114:117], v[168:171], v[176:179], v[114:117]
	v_mfma_f32_16x16x32_bf16 v[102:105], v[160:163], v[184:187], v[102:105]
	v_mfma_f32_16x16x32_bf16 v[98:101], v[168:171], v[184:187], v[98:101]
	v_mfma_f32_16x16x32_bf16 v[86:89], v[160:163], v[196:199], v[86:89]
	v_mfma_f32_16x16x32_bf16 v[82:85], v[168:171], v[196:199], v[82:85]
	v_mfma_f32_16x16x32_bf16 v[70:73], v[160:163], v[204:207], v[70:73]
	v_mfma_f32_16x16x32_bf16 v[66:69], v[168:171], v[204:207], v[66:69]
	v_mfma_f32_16x16x32_bf16 v[118:121], v[164:167], v[180:183], v[118:121]
	v_mfma_f32_16x16x32_bf16 v[114:117], v[172:175], v[180:183], v[114:117]
	v_mfma_f32_16x16x32_bf16 v[102:105], v[164:167], v[192:195], v[102:105]
	v_mfma_f32_16x16x32_bf16 v[98:101], v[172:175], v[192:195], v[98:101]
	v_mfma_f32_16x16x32_bf16 v[86:89], v[164:167], v[200:203], v[86:89]
	v_mfma_f32_16x16x32_bf16 v[82:85], v[172:175], v[200:203], v[82:85]
	v_mfma_f32_16x16x32_bf16 v[70:73], v[164:167], v[208:211], v[70:73]
	v_mfma_f32_16x16x32_bf16 v[66:69], v[172:175], v[208:211], v[66:69]
	s_setprio 0
	s_barrier
	s_add_i32 s1, s1, s4
	v_lshl_add_u64 v[212:213], v[212:213], 0, s[6:7]
	s_mov_b32 m0, s1
	ds_read_b128 v[176:179], v143 offset:49152
	ds_read_b128 v[180:183], v143 offset:50176
	ds_read_b128 v[184:187], v143 offset:51200
	ds_read_b128 v[192:195], v143 offset:52224
	ds_read_b128 v[196:199], v143 offset:53248
	ds_read_b128 v[200:203], v143 offset:54272
	ds_read_b128 v[204:207], v143 offset:55296
	ds_read_b128 v[208:211], v143 offset:56320
	global_load_lds_dwordx4 v[212:213], off
	v_lshl_add_u64 v[212:213], v[214:215], 0, s[6:7]
	s_add_i32 m0, s1, 0x2000
	s_add_i32 s1, s63, s4
	global_load_lds_dwordx4 v[212:213], off
	v_lshl_add_u64 v[212:213], v[216:217], 0, s[6:7]
	s_mov_b32 m0, s1
	s_nop 0
	v_lshl_add_u64 v[212:213], v[238:239], 0, s[6:7]
	s_add_i32 m0, s1, 0x2000
	s_nop 0
	v_lshl_add_u64 v[212:213], v[240:241], 0, s[6:7]
	s_mov_b32 m0, s57
	s_nop 0
	global_load_lds_dwordx4 v[212:213], off
	v_lshl_add_u64 v[212:213], v[244:245], 0, s[6:7]
	s_mov_b32 m0, s58
	s_nop 0
	global_load_lds_dwordx4 v[212:213], off
	s_waitcnt vmcnt(6)
	s_waitcnt lgkmcnt(0)
	s_barrier
	s_setprio 1
	s_waitcnt lgkmcnt(0)
	v_mfma_f32_16x16x32_bf16 v[62:65], v[144:147], v[176:179], v[62:65]
	v_mfma_f32_16x16x32_bf16 v[58:61], v[152:155], v[176:179], v[58:61]
	v_mfma_f32_16x16x32_bf16 v[46:49], v[144:147], v[184:187], v[46:49]
	v_mfma_f32_16x16x32_bf16 v[42:45], v[152:155], v[184:187], v[42:45]
	v_mfma_f32_16x16x32_bf16 v[30:33], v[144:147], v[196:199], v[30:33]
	v_mfma_f32_16x16x32_bf16 v[26:29], v[152:155], v[196:199], v[26:29]
	v_mfma_f32_16x16x32_bf16 v[14:17], v[144:147], v[204:207], v[14:17]
	v_mfma_f32_16x16x32_bf16 v[10:13], v[152:155], v[204:207], v[10:13]
	v_mfma_f32_16x16x32_bf16 v[62:65], v[148:151], v[180:183], v[62:65]
	v_mfma_f32_16x16x32_bf16 v[58:61], v[156:159], v[180:183], v[58:61]
	v_mfma_f32_16x16x32_bf16 v[46:49], v[148:151], v[192:195], v[46:49]
	v_mfma_f32_16x16x32_bf16 v[42:45], v[156:159], v[192:195], v[42:45]
	v_mfma_f32_16x16x32_bf16 v[30:33], v[148:151], v[200:203], v[30:33]
	v_mfma_f32_16x16x32_bf16 v[26:29], v[156:159], v[200:203], v[26:29]
	v_mfma_f32_16x16x32_bf16 v[14:17], v[148:151], v[208:211], v[14:17]
	v_mfma_f32_16x16x32_bf16 v[10:13], v[156:159], v[208:211], v[10:13]
	s_setprio 0
	s_setprio 1
	v_mfma_f32_16x16x32_bf16 v[54:57], v[160:163], v[176:179], v[54:57]
	v_mfma_f32_16x16x32_bf16 v[50:53], v[168:171], v[176:179], v[50:53]
	v_mfma_f32_16x16x32_bf16 v[38:41], v[160:163], v[184:187], v[38:41]
	v_mfma_f32_16x16x32_bf16 v[34:37], v[168:171], v[184:187], v[34:37]
	v_mfma_f32_16x16x32_bf16 v[22:25], v[160:163], v[196:199], v[22:25]
	v_mfma_f32_16x16x32_bf16 v[18:21], v[168:171], v[196:199], v[18:21]
	v_mfma_f32_16x16x32_bf16 v[6:9], v[160:163], v[204:207], v[6:9]
	v_mfma_f32_16x16x32_bf16 v[2:5], v[168:171], v[204:207], v[2:5]
	v_mfma_f32_16x16x32_bf16 v[54:57], v[164:167], v[180:183], v[54:57]
	v_mfma_f32_16x16x32_bf16 v[50:53], v[172:175], v[180:183], v[50:53]
	v_mfma_f32_16x16x32_bf16 v[38:41], v[164:167], v[192:195], v[38:41]
	v_mfma_f32_16x16x32_bf16 v[34:37], v[172:175], v[192:195], v[34:37]
	v_mfma_f32_16x16x32_bf16 v[22:25], v[164:167], v[200:203], v[22:25]
	v_mfma_f32_16x16x32_bf16 v[18:21], v[172:175], v[200:203], v[18:21]
	v_mfma_f32_16x16x32_bf16 v[6:9], v[164:167], v[208:211], v[6:9]
	v_mfma_f32_16x16x32_bf16 v[2:5], v[172:175], v[208:211], v[2:5]
	s_setprio 0
	s_barrier
	s_cmp_ge_i32 s62, s59
	s_mov_b64 s[48:49], s[50:51]
	s_mov_b32 s52, s62
	s_cbranch_scc0 .LBB0_435
